# GEMM K-loop MFMA segments: accumulate-chain pairs visited in a serpentine over the (A,B) sub-tile grid with alternating k-step order, so each MFMA shares C or one A/B operand register with its predece
# speedup vs baseline: 1.0213x; 1.0086x over previous
.LBB0_159:
	s_ashr_i32 s29, s28, 31
	s_lshl_b64 s[24:25], s[28:29], 19
	s_add_u32 s24, s34, s24
	s_addc_u32 s25, s35, s25
	s_and_b64 s[30:31], s[18:19], exec
	s_cselect_b32 s29, s25, s41
	s_cselect_b32 s43, s24, s40
	s_ashr_i32 s21, s20, 31
	s_lshl_b64 s[30:31], s[20:21], 19
	s_add_u32 s30, s36, s30
	s_addc_u32 s31, s37, s31
	s_and_b64 s[56:57], s[18:19], exec
	s_cselect_b32 s21, s31, s27
	s_cselect_b32 s55, s30, s26
	s_add_u32 s40, s40, 0x40080
	s_addc_u32 s41, s41, 0
	s_add_u32 s56, s26, 0x100
	s_addc_u32 s57, s27, 0
	s_mov_b32 s58, -2
	s_add_u32 s26, s40, 0xfffc0080
	s_addc_u32 s27, s41, -1
	s_add_i32 s59, 0, 0x10000
	s_cmp_eq_u32 s58, 12
	s_cselect_b32 vcc_hi, s29, s27
	s_cselect_b32 vcc_lo, s43, s26
	v_add_u32_e32 v0, s59, v167
	s_cselect_b32 s27, s21, s57
	s_cselect_b32 s26, s55, s56
	s_add_i32 s62, 0, 0x14000
	ds_read_b128 v[142:145], v0
	ds_read_b128 v[146:149], v0 offset:1024
	ds_read_b128 v[150:153], v0 offset:2048
	ds_read_b128 v[154:157], v0 offset:3072
	v_add_u32_e32 v0, s62, v167
	ds_read_b128 v[158:161], v0
	ds_read_b128 v[162:165], v0 offset:1024
	ds_read_b128 v[174:177], v0 offset:2048
	ds_read_b128 v[178:181], v0 offset:3072
	v_lshl_add_u64 v[214:215], s[40:41], 0, v[138:139]
	s_add_i32 m0, s23, 0xc000
	ds_read_b128 v[182:185], v173
	ds_read_b128 v[186:189], v173 offset:1024
	ds_read_b128 v[190:193], v173 offset:2048
	ds_read_b128 v[194:197], v173 offset:3072
	ds_read_b128 v[198:201], v173 offset:4096
	ds_read_b128 v[202:205], v173 offset:5120
	ds_read_b128 v[206:209], v173 offset:6144
	ds_read_b128 v[210:213], v173 offset:7168
	global_load_lds_dwordx4 v[214:215], off
	v_lshl_add_u64 v[214:215], s[40:41], 0, v[140:141]
	s_add_i32 m0, s23, 0xe000
	s_nop 0
	global_load_lds_dwordx4 v[214:215], off
	s_waitcnt vmcnt(8)
	s_waitcnt lgkmcnt(0)
	s_barrier
	s_waitcnt lgkmcnt(0)
	v_mfma_f32_16x16x32_bf16 v[126:129], v[142:145], v[182:185], 0
	v_mfma_f32_16x16x32_bf16 v[126:129], v[146:149], v[186:189], v[126:129]
	v_mfma_f32_16x16x32_bf16 v[122:125], v[154:157], v[186:189], 0
	v_mfma_f32_16x16x32_bf16 v[122:125], v[150:153], v[182:185], v[122:125]
	v_mfma_f32_16x16x32_bf16 v[114:117], v[150:153], v[190:193], 0
	v_mfma_f32_16x16x32_bf16 v[114:117], v[154:157], v[194:197], v[114:117]
	v_mfma_f32_16x16x32_bf16 v[118:121], v[146:149], v[194:197], 0
	v_mfma_f32_16x16x32_bf16 v[118:121], v[142:145], v[190:193], v[118:121]
	v_mfma_f32_16x16x32_bf16 v[110:113], v[142:145], v[198:201], 0
	v_mfma_f32_16x16x32_bf16 v[110:113], v[146:149], v[202:205], v[110:113]
	v_mfma_f32_16x16x32_bf16 v[106:109], v[154:157], v[202:205], 0
	v_mfma_f32_16x16x32_bf16 v[106:109], v[150:153], v[198:201], v[106:109]
	v_mfma_f32_16x16x32_bf16 v[98:101], v[150:153], v[206:209], 0
	v_mfma_f32_16x16x32_bf16 v[98:101], v[154:157], v[210:213], v[98:101]
	v_mfma_f32_16x16x32_bf16 v[102:105], v[146:149], v[210:213], 0
	v_mfma_f32_16x16x32_bf16 v[102:105], v[142:145], v[206:209], v[102:105]
	v_mfma_f32_16x16x32_bf16 v[38:41], v[158:161], v[206:209], 0
	v_mfma_f32_16x16x32_bf16 v[38:41], v[162:165], v[210:213], v[38:41]
	v_mfma_f32_16x16x32_bf16 v[34:37], v[178:181], v[210:213], 0
	v_mfma_f32_16x16x32_bf16 v[34:37], v[174:177], v[206:209], v[34:37]
	v_mfma_f32_16x16x32_bf16 v[46:49], v[174:177], v[198:201], 0
	v_mfma_f32_16x16x32_bf16 v[46:49], v[178:181], v[202:205], v[46:49]
	v_mfma_f32_16x16x32_bf16 v[54:57], v[162:165], v[202:205], 0
	v_mfma_f32_16x16x32_bf16 v[54:57], v[158:161], v[198:201], v[54:57]
	v_mfma_f32_16x16x32_bf16 v[70:73], v[158:161], v[190:193], 0
	v_mfma_f32_16x16x32_bf16 v[70:73], v[162:165], v[194:197], v[70:73]
	v_mfma_f32_16x16x32_bf16 v[62:65], v[178:181], v[194:197], 0
	v_mfma_f32_16x16x32_bf16 v[62:65], v[174:177], v[190:193], v[62:65]
	v_mfma_f32_16x16x32_bf16 v[74:77], v[174:177], v[182:185], 0
	v_mfma_f32_16x16x32_bf16 v[74:77], v[178:181], v[186:189], v[74:77]
	v_mfma_f32_16x16x32_bf16 v[82:85], v[162:165], v[186:189], 0
	v_mfma_f32_16x16x32_bf16 v[82:85], v[158:161], v[182:185], v[82:85]
	s_barrier
	s_add_i32 s59, s59, s44
	v_lshl_add_u64 v[214:215], s[26:27], 0, v[132:133]
	s_mov_b32 m0, s59
	ds_read_b128 v[182:185], v173 offset:16384
	ds_read_b128 v[186:189], v173 offset:17408
	ds_read_b128 v[190:193], v173 offset:18432
	ds_read_b128 v[194:197], v173 offset:19456
	ds_read_b128 v[198:201], v173 offset:20480
	ds_read_b128 v[202:205], v173 offset:21504
	ds_read_b128 v[206:209], v173 offset:22528
	ds_read_b128 v[210:213], v173 offset:23552
	global_load_lds_dwordx4 v[214:215], off
	s_add_i32 m0, s59, 0x2000
	s_add_u32 s60, s26, 0x40000
	v_lshl_add_u64 v[216:217], s[26:27], 0, v[136:137]
	s_addc_u32 s61, s27, 0
	s_add_i32 s59, s62, s44
	global_load_lds_dwordx4 v[216:217], off
	v_lshl_add_u64 v[218:219], s[60:61], 0, v[132:133]
	s_mov_b32 m0, s59
	v_lshl_add_u64 v[220:221], vcc, 0, v[134:135]
	global_load_lds_dwordx4 v[218:219], off
	v_lshl_add_u64 v[218:219], s[60:61], 0, v[136:137]
	s_add_i32 m0, s59, 0x2000
	s_nop 0
	global_load_lds_dwordx4 v[218:219], off
	v_lshl_add_u64 v[218:219], vcc, 0, v[130:131]
	s_mov_b32 m0, s23
	s_nop 0
	global_load_lds_dwordx4 v[218:219], off
	s_mov_b32 m0, s45
	s_nop 0
	global_load_lds_dwordx4 v[220:221], off
	s_waitcnt vmcnt(8)
	s_waitcnt lgkmcnt(0)
	s_barrier
	s_waitcnt lgkmcnt(0)
	v_mfma_f32_16x16x32_bf16 v[94:97], v[142:145], v[182:185], 0
	v_mfma_f32_16x16x32_bf16 v[94:97], v[146:149], v[186:189], v[94:97]
	v_mfma_f32_16x16x32_bf16 v[90:93], v[154:157], v[186:189], 0
	v_mfma_f32_16x16x32_bf16 v[90:93], v[150:153], v[182:185], v[90:93]
	v_mfma_f32_16x16x32_bf16 v[78:81], v[150:153], v[190:193], 0
	v_mfma_f32_16x16x32_bf16 v[78:81], v[154:157], v[194:197], v[78:81]
	v_mfma_f32_16x16x32_bf16 v[86:89], v[146:149], v[194:197], 0
	v_mfma_f32_16x16x32_bf16 v[86:89], v[142:145], v[190:193], v[86:89]
	v_mfma_f32_16x16x32_bf16 v[66:69], v[142:145], v[198:201], 0
	v_mfma_f32_16x16x32_bf16 v[66:69], v[146:149], v[202:205], v[66:69]
	v_mfma_f32_16x16x32_bf16 v[58:61], v[154:157], v[202:205], 0
	v_mfma_f32_16x16x32_bf16 v[58:61], v[150:153], v[198:201], v[58:61]
	v_mfma_f32_16x16x32_bf16 v[42:45], v[150:153], v[206:209], 0
	v_mfma_f32_16x16x32_bf16 v[42:45], v[154:157], v[210:213], v[42:45]
	v_mfma_f32_16x16x32_bf16 v[50:53], v[146:149], v[210:213], 0
	v_mfma_f32_16x16x32_bf16 v[50:53], v[142:145], v[206:209], v[50:53]
	v_mfma_f32_16x16x32_bf16 v[6:9], v[158:161], v[206:209], 0
	v_mfma_f32_16x16x32_bf16 v[6:9], v[162:165], v[210:213], v[6:9]
	v_mfma_f32_16x16x32_bf16 v[2:5], v[178:181], v[210:213], 0
	v_mfma_f32_16x16x32_bf16 v[2:5], v[174:177], v[206:209], v[2:5]
	v_mfma_f32_16x16x32_bf16 v[10:13], v[174:177], v[198:201], 0
	v_mfma_f32_16x16x32_bf16 v[10:13], v[178:181], v[202:205], v[10:13]
	v_mfma_f32_16x16x32_bf16 v[14:17], v[162:165], v[202:205], 0
	v_mfma_f32_16x16x32_bf16 v[14:17], v[158:161], v[198:201], v[14:17]
	v_mfma_f32_16x16x32_bf16 v[22:25], v[158:161], v[190:193], 0
	v_mfma_f32_16x16x32_bf16 v[22:25], v[162:165], v[194:197], v[22:25]
	v_mfma_f32_16x16x32_bf16 v[18:21], v[178:181], v[194:197], 0
	v_mfma_f32_16x16x32_bf16 v[18:21], v[174:177], v[190:193], v[18:21]
	v_mfma_f32_16x16x32_bf16 v[26:29], v[174:177], v[182:185], 0
	v_mfma_f32_16x16x32_bf16 v[26:29], v[178:181], v[186:189], v[26:29]
	v_mfma_f32_16x16x32_bf16 v[30:33], v[162:165], v[186:189], 0
	v_mfma_f32_16x16x32_bf16 v[30:33], v[158:161], v[182:185], v[30:33]
	s_barrier
	s_add_i32 s59, 0, 0x18000
	v_add_u32_e32 v0, s59, v167
	s_add_i32 s62, 0, 0x1c000
	ds_read_b128 v[142:145], v0
	ds_read_b128 v[146:149], v0 offset:1024
	ds_read_b128 v[150:153], v0 offset:2048
	ds_read_b128 v[154:157], v0 offset:3072
	v_add_u32_e32 v0, s62, v167
	ds_read_b128 v[158:161], v0
	ds_read_b128 v[162:165], v0 offset:1024
	ds_read_b128 v[174:177], v0 offset:2048
	ds_read_b128 v[178:181], v0 offset:3072
	s_add_u32 s60, vcc_lo, 0x40000
	s_addc_u32 s61, vcc_hi, 0
	s_mov_b32 m0, s47
	v_lshl_add_u64 v[222:223], s[60:61], 0, v[130:131]
	ds_read_b128 v[182:185], v173 offset:32768
	ds_read_b128 v[186:189], v173 offset:33792
	ds_read_b128 v[190:193], v173 offset:34816
	ds_read_b128 v[194:197], v173 offset:35840
	ds_read_b128 v[198:201], v173 offset:36864
	ds_read_b128 v[202:205], v173 offset:37888
	ds_read_b128 v[206:209], v173 offset:38912
	ds_read_b128 v[210:213], v173 offset:39936
	global_load_lds_dwordx4 v[222:223], off
	v_lshl_add_u64 v[222:223], s[60:61], 0, v[134:135]
	s_mov_b32 m0, s49
	s_nop 0
	global_load_lds_dwordx4 v[222:223], off
	s_waitcnt vmcnt(8)
	s_waitcnt lgkmcnt(0)
	s_barrier
	s_waitcnt lgkmcnt(0)
	v_mfma_f32_16x16x32_bf16 v[126:129], v[142:145], v[182:185], v[126:129]
	v_mfma_f32_16x16x32_bf16 v[126:129], v[146:149], v[186:189], v[126:129]
	v_mfma_f32_16x16x32_bf16 v[122:125], v[154:157], v[186:189], v[122:125]
	v_mfma_f32_16x16x32_bf16 v[122:125], v[150:153], v[182:185], v[122:125]
	v_mfma_f32_16x16x32_bf16 v[114:117], v[150:153], v[190:193], v[114:117]
	v_mfma_f32_16x16x32_bf16 v[114:117], v[154:157], v[194:197], v[114:117]
	v_mfma_f32_16x16x32_bf16 v[118:121], v[146:149], v[194:197], v[118:121]
	v_mfma_f32_16x16x32_bf16 v[118:121], v[142:145], v[190:193], v[118:121]
	v_mfma_f32_16x16x32_bf16 v[110:113], v[142:145], v[198:201], v[110:113]
	v_mfma_f32_16x16x32_bf16 v[110:113], v[146:149], v[202:205], v[110:113]
	v_mfma_f32_16x16x32_bf16 v[106:109], v[154:157], v[202:205], v[106:109]
	v_mfma_f32_16x16x32_bf16 v[106:109], v[150:153], v[198:201], v[106:109]
	v_mfma_f32_16x16x32_bf16 v[98:101], v[150:153], v[206:209], v[98:101]
	v_mfma_f32_16x16x32_bf16 v[98:101], v[154:157], v[210:213], v[98:101]
	v_mfma_f32_16x16x32_bf16 v[102:105], v[146:149], v[210:213], v[102:105]
	v_mfma_f32_16x16x32_bf16 v[102:105], v[142:145], v[206:209], v[102:105]
	v_mfma_f32_16x16x32_bf16 v[38:41], v[158:161], v[206:209], v[38:41]
	v_mfma_f32_16x16x32_bf16 v[38:41], v[162:165], v[210:213], v[38:41]
	v_mfma_f32_16x16x32_bf16 v[34:37], v[178:181], v[210:213], v[34:37]
	v_mfma_f32_16x16x32_bf16 v[34:37], v[174:177], v[206:209], v[34:37]
	v_mfma_f32_16x16x32_bf16 v[46:49], v[174:177], v[198:201], v[46:49]
	v_mfma_f32_16x16x32_bf16 v[46:49], v[178:181], v[202:205], v[46:49]
	v_mfma_f32_16x16x32_bf16 v[54:57], v[162:165], v[202:205], v[54:57]
	v_mfma_f32_16x16x32_bf16 v[54:57], v[158:161], v[198:201], v[54:57]
	v_mfma_f32_16x16x32_bf16 v[70:73], v[158:161], v[190:193], v[70:73]
	v_mfma_f32_16x16x32_bf16 v[70:73], v[162:165], v[194:197], v[70:73]
	v_mfma_f32_16x16x32_bf16 v[62:65], v[178:181], v[194:197], v[62:65]
	v_mfma_f32_16x16x32_bf16 v[62:65], v[174:177], v[190:193], v[62:65]
	v_mfma_f32_16x16x32_bf16 v[74:77], v[174:177], v[182:185], v[74:77]
	v_mfma_f32_16x16x32_bf16 v[74:77], v[178:181], v[186:189], v[74:77]
	v_mfma_f32_16x16x32_bf16 v[82:85], v[162:165], v[186:189], v[82:85]
	v_mfma_f32_16x16x32_bf16 v[82:85], v[158:161], v[182:185], v[82:85]
	s_barrier
	s_add_i32 s59, s59, s44
	v_lshl_add_u64 v[214:215], v[214:215], 0, s[98:99]
	s_mov_b32 m0, s59
	ds_read_b128 v[182:185], v173 offset:49152
	ds_read_b128 v[186:189], v173 offset:50176
	ds_read_b128 v[190:193], v173 offset:51200
	ds_read_b128 v[194:197], v173 offset:52224
	ds_read_b128 v[198:201], v173 offset:53248
	ds_read_b128 v[202:205], v173 offset:54272
	ds_read_b128 v[206:209], v173 offset:55296
	ds_read_b128 v[210:213], v173 offset:56320
	global_load_lds_dwordx4 v[214:215], off
	s_add_i32 m0, s59, 0x2000
	s_add_u32 s26, s26, 0x40080
	v_lshl_add_u64 v[214:215], v[216:217], 0, s[98:99]
	s_addc_u32 s27, s27, 0
	s_add_i32 s59, s62, s44
	global_load_lds_dwordx4 v[214:215], off
	v_lshl_add_u64 v[214:215], s[26:27], 0, v[132:133]
	s_mov_b32 m0, s59
	s_nop 0
	global_load_lds_dwordx4 v[214:215], off
	v_lshl_add_u64 v[214:215], s[26:27], 0, v[136:137]
	s_add_i32 m0, s59, 0x2000
	s_nop 0
	global_load_lds_dwordx4 v[214:215], off
	v_lshl_add_u64 v[214:215], v[218:219], 0, s[98:99]
	s_mov_b32 m0, s52
	s_nop 0
	global_load_lds_dwordx4 v[214:215], off
	v_lshl_add_u64 v[214:215], v[220:221], 0, s[98:99]
	s_mov_b32 m0, s53
	s_nop 0
	global_load_lds_dwordx4 v[214:215], off
	s_waitcnt vmcnt(8)
	s_waitcnt lgkmcnt(0)
	s_barrier
	s_waitcnt lgkmcnt(0)
	v_mfma_f32_16x16x32_bf16 v[94:97], v[142:145], v[182:185], v[94:97]
	v_mfma_f32_16x16x32_bf16 v[94:97], v[146:149], v[186:189], v[94:97]
	v_mfma_f32_16x16x32_bf16 v[90:93], v[154:157], v[186:189], v[90:93]
	v_mfma_f32_16x16x32_bf16 v[90:93], v[150:153], v[182:185], v[90:93]
	v_mfma_f32_16x16x32_bf16 v[78:81], v[150:153], v[190:193], v[78:81]
	v_mfma_f32_16x16x32_bf16 v[78:81], v[154:157], v[194:197], v[78:81]
	v_mfma_f32_16x16x32_bf16 v[86:89], v[146:149], v[194:197], v[86:89]
	v_mfma_f32_16x16x32_bf16 v[86:89], v[142:145], v[190:193], v[86:89]
	v_mfma_f32_16x16x32_bf16 v[66:69], v[142:145], v[198:201], v[66:69]
	v_mfma_f32_16x16x32_bf16 v[66:69], v[146:149], v[202:205], v[66:69]
	v_mfma_f32_16x16x32_bf16 v[58:61], v[154:157], v[202:205], v[58:61]
	v_mfma_f32_16x16x32_bf16 v[58:61], v[150:153], v[198:201], v[58:61]
	v_mfma_f32_16x16x32_bf16 v[42:45], v[150:153], v[206:209], v[42:45]
	v_mfma_f32_16x16x32_bf16 v[42:45], v[154:157], v[210:213], v[42:45]
	v_mfma_f32_16x16x32_bf16 v[50:53], v[146:149], v[210:213], v[50:53]
	v_mfma_f32_16x16x32_bf16 v[50:53], v[142:145], v[206:209], v[50:53]
	v_mfma_f32_16x16x32_bf16 v[6:9], v[158:161], v[206:209], v[6:9]
	v_mfma_f32_16x16x32_bf16 v[6:9], v[162:165], v[210:213], v[6:9]
	v_mfma_f32_16x16x32_bf16 v[2:5], v[178:181], v[210:213], v[2:5]
	v_mfma_f32_16x16x32_bf16 v[2:5], v[174:177], v[206:209], v[2:5]
	v_mfma_f32_16x16x32_bf16 v[10:13], v[174:177], v[198:201], v[10:13]
	v_mfma_f32_16x16x32_bf16 v[10:13], v[178:181], v[202:205], v[10:13]
	v_mfma_f32_16x16x32_bf16 v[14:17], v[162:165], v[202:205], v[14:17]
	v_mfma_f32_16x16x32_bf16 v[14:17], v[158:161], v[198:201], v[14:17]
	v_mfma_f32_16x16x32_bf16 v[22:25], v[158:161], v[190:193], v[22:25]
	v_mfma_f32_16x16x32_bf16 v[22:25], v[162:165], v[194:197], v[22:25]
	v_mfma_f32_16x16x32_bf16 v[18:21], v[178:181], v[194:197], v[18:21]
	v_mfma_f32_16x16x32_bf16 v[18:21], v[174:177], v[190:193], v[18:21]
	v_mfma_f32_16x16x32_bf16 v[26:29], v[174:177], v[182:185], v[26:29]
	v_mfma_f32_16x16x32_bf16 v[26:29], v[178:181], v[186:189], v[26:29]
	v_mfma_f32_16x16x32_bf16 v[30:33], v[162:165], v[186:189], v[30:33]
	v_mfma_f32_16x16x32_bf16 v[30:33], v[158:161], v[182:185], v[30:33]
	s_barrier
	s_add_i32 s58, s58, 2
	s_add_u32 s40, s40, 0x100
	s_addc_u32 s41, s41, 0
	s_add_u32 s56, s56, 0x100
	s_addc_u32 s57, s57, 0
	s_cmp_gt_u32 s58, 13
	s_cbranch_scc1 .Lpeel_done_160
.LBB0_160:
	s_add_u32 s26, s40, 0xfffc0080
	s_addc_u32 s27, s41, -1
	s_add_i32 s59, 0, 0x10000
	s_cmp_eq_u32 s58, 12
	s_cselect_b32 vcc_hi, s29, s27
	s_cselect_b32 vcc_lo, s43, s26
	v_add_u32_e32 v0, s59, v167
	s_cselect_b32 s27, s21, s57
	s_cselect_b32 s26, s55, s56
	s_add_i32 s62, 0, 0x14000
	ds_read_b128 v[142:145], v0
	ds_read_b128 v[146:149], v0 offset:1024
	ds_read_b128 v[150:153], v0 offset:2048
	ds_read_b128 v[154:157], v0 offset:3072
	v_add_u32_e32 v0, s62, v167
	ds_read_b128 v[158:161], v0
	ds_read_b128 v[162:165], v0 offset:1024
	ds_read_b128 v[174:177], v0 offset:2048
	ds_read_b128 v[178:181], v0 offset:3072
	v_lshl_add_u64 v[214:215], s[40:41], 0, v[138:139]
	s_add_i32 m0, s23, 0xc000
	ds_read_b128 v[182:185], v173
	ds_read_b128 v[186:189], v173 offset:1024
	ds_read_b128 v[190:193], v173 offset:2048
	ds_read_b128 v[194:197], v173 offset:3072
	ds_read_b128 v[198:201], v173 offset:4096
	ds_read_b128 v[202:205], v173 offset:5120
	ds_read_b128 v[206:209], v173 offset:6144
	ds_read_b128 v[210:213], v173 offset:7168
	global_load_lds_dwordx4 v[214:215], off
	v_lshl_add_u64 v[214:215], s[40:41], 0, v[140:141]
	s_add_i32 m0, s23, 0xe000
	s_nop 0
	global_load_lds_dwordx4 v[214:215], off
	s_waitcnt vmcnt(8)
	s_waitcnt lgkmcnt(0)
	s_barrier
	s_waitcnt lgkmcnt(0)
	v_mfma_f32_16x16x32_bf16 v[126:129], v[142:145], v[182:185], v[126:129]
	v_mfma_f32_16x16x32_bf16 v[126:129], v[146:149], v[186:189], v[126:129]
	v_mfma_f32_16x16x32_bf16 v[122:125], v[154:157], v[186:189], v[122:125]
	v_mfma_f32_16x16x32_bf16 v[122:125], v[150:153], v[182:185], v[122:125]
	v_mfma_f32_16x16x32_bf16 v[114:117], v[150:153], v[190:193], v[114:117]
	v_mfma_f32_16x16x32_bf16 v[114:117], v[154:157], v[194:197], v[114:117]
	v_mfma_f32_16x16x32_bf16 v[118:121], v[146:149], v[194:197], v[118:121]
	v_mfma_f32_16x16x32_bf16 v[118:121], v[142:145], v[190:193], v[118:121]
	v_mfma_f32_16x16x32_bf16 v[110:113], v[142:145], v[198:201], v[110:113]
	v_mfma_f32_16x16x32_bf16 v[110:113], v[146:149], v[202:205], v[110:113]
	v_mfma_f32_16x16x32_bf16 v[106:109], v[154:157], v[202:205], v[106:109]
	v_mfma_f32_16x16x32_bf16 v[106:109], v[150:153], v[198:201], v[106:109]
	v_mfma_f32_16x16x32_bf16 v[98:101], v[150:153], v[206:209], v[98:101]
	v_mfma_f32_16x16x32_bf16 v[98:101], v[154:157], v[210:213], v[98:101]
	v_mfma_f32_16x16x32_bf16 v[102:105], v[146:149], v[210:213], v[102:105]
	v_mfma_f32_16x16x32_bf16 v[102:105], v[142:145], v[206:209], v[102:105]
	v_mfma_f32_16x16x32_bf16 v[38:41], v[158:161], v[206:209], v[38:41]
	v_mfma_f32_16x16x32_bf16 v[38:41], v[162:165], v[210:213], v[38:41]
	v_mfma_f32_16x16x32_bf16 v[34:37], v[178:181], v[210:213], v[34:37]
	v_mfma_f32_16x16x32_bf16 v[34:37], v[174:177], v[206:209], v[34:37]
	v_mfma_f32_16x16x32_bf16 v[46:49], v[174:177], v[198:201], v[46:49]
	v_mfma_f32_16x16x32_bf16 v[46:49], v[178:181], v[202:205], v[46:49]
	v_mfma_f32_16x16x32_bf16 v[54:57], v[162:165], v[202:205], v[54:57]
	v_mfma_f32_16x16x32_bf16 v[54:57], v[158:161], v[198:201], v[54:57]
	v_mfma_f32_16x16x32_bf16 v[70:73], v[158:161], v[190:193], v[70:73]
	v_mfma_f32_16x16x32_bf16 v[70:73], v[162:165], v[194:197], v[70:73]
	v_mfma_f32_16x16x32_bf16 v[62:65], v[178:181], v[194:197], v[62:65]
	v_mfma_f32_16x16x32_bf16 v[62:65], v[174:177], v[190:193], v[62:65]
	v_mfma_f32_16x16x32_bf16 v[74:77], v[174:177], v[182:185], v[74:77]
	v_mfma_f32_16x16x32_bf16 v[74:77], v[178:181], v[186:189], v[74:77]
	v_mfma_f32_16x16x32_bf16 v[82:85], v[162:165], v[186:189], v[82:85]
	v_mfma_f32_16x16x32_bf16 v[82:85], v[158:161], v[182:185], v[82:85]
	s_barrier
	s_add_i32 s59, s59, s44
	v_lshl_add_u64 v[214:215], s[26:27], 0, v[132:133]
	s_mov_b32 m0, s59
	ds_read_b128 v[182:185], v173 offset:16384
	ds_read_b128 v[186:189], v173 offset:17408
	ds_read_b128 v[190:193], v173 offset:18432
	ds_read_b128 v[194:197], v173 offset:19456
	ds_read_b128 v[198:201], v173 offset:20480
	ds_read_b128 v[202:205], v173 offset:21504
	ds_read_b128 v[206:209], v173 offset:22528
	ds_read_b128 v[210:213], v173 offset:23552
	global_load_lds_dwordx4 v[214:215], off
	s_add_i32 m0, s59, 0x2000
	s_add_u32 s60, s26, 0x40000
	v_lshl_add_u64 v[216:217], s[26:27], 0, v[136:137]
	s_addc_u32 s61, s27, 0
	s_add_i32 s59, s62, s44
	global_load_lds_dwordx4 v[216:217], off
	v_lshl_add_u64 v[218:219], s[60:61], 0, v[132:133]
	s_mov_b32 m0, s59
	v_lshl_add_u64 v[220:221], vcc, 0, v[134:135]
	global_load_lds_dwordx4 v[218:219], off
	v_lshl_add_u64 v[218:219], s[60:61], 0, v[136:137]
	s_add_i32 m0, s59, 0x2000
	s_nop 0
	global_load_lds_dwordx4 v[218:219], off
	v_lshl_add_u64 v[218:219], vcc, 0, v[130:131]
	s_mov_b32 m0, s23
	s_nop 0
	global_load_lds_dwordx4 v[218:219], off
	s_mov_b32 m0, s45
	s_nop 0
	global_load_lds_dwordx4 v[220:221], off
	s_waitcnt vmcnt(8)
	s_waitcnt lgkmcnt(0)
	s_barrier
	s_waitcnt lgkmcnt(0)
	v_mfma_f32_16x16x32_bf16 v[94:97], v[142:145], v[182:185], v[94:97]
	v_mfma_f32_16x16x32_bf16 v[94:97], v[146:149], v[186:189], v[94:97]
	v_mfma_f32_16x16x32_bf16 v[90:93], v[154:157], v[186:189], v[90:93]
	v_mfma_f32_16x16x32_bf16 v[90:93], v[150:153], v[182:185], v[90:93]
	v_mfma_f32_16x16x32_bf16 v[78:81], v[150:153], v[190:193], v[78:81]
	v_mfma_f32_16x16x32_bf16 v[78:81], v[154:157], v[194:197], v[78:81]
	v_mfma_f32_16x16x32_bf16 v[86:89], v[146:149], v[194:197], v[86:89]
	v_mfma_f32_16x16x32_bf16 v[86:89], v[142:145], v[190:193], v[86:89]
	v_mfma_f32_16x16x32_bf16 v[66:69], v[142:145], v[198:201], v[66:69]
	v_mfma_f32_16x16x32_bf16 v[66:69], v[146:149], v[202:205], v[66:69]
	v_mfma_f32_16x16x32_bf16 v[58:61], v[154:157], v[202:205], v[58:61]
	v_mfma_f32_16x16x32_bf16 v[58:61], v[150:153], v[198:201], v[58:61]
	v_mfma_f32_16x16x32_bf16 v[42:45], v[150:153], v[206:209], v[42:45]
	v_mfma_f32_16x16x32_bf16 v[42:45], v[154:157], v[210:213], v[42:45]
	v_mfma_f32_16x16x32_bf16 v[50:53], v[146:149], v[210:213], v[50:53]
	v_mfma_f32_16x16x32_bf16 v[50:53], v[142:145], v[206:209], v[50:53]
	v_mfma_f32_16x16x32_bf16 v[6:9], v[158:161], v[206:209], v[6:9]
	v_mfma_f32_16x16x32_bf16 v[6:9], v[162:165], v[210:213], v[6:9]
	v_mfma_f32_16x16x32_bf16 v[2:5], v[178:181], v[210:213], v[2:5]
	v_mfma_f32_16x16x32_bf16 v[2:5], v[174:177], v[206:209], v[2:5]
	v_mfma_f32_16x16x32_bf16 v[10:13], v[174:177], v[198:201], v[10:13]
	v_mfma_f32_16x16x32_bf16 v[10:13], v[178:181], v[202:205], v[10:13]
	v_mfma_f32_16x16x32_bf16 v[14:17], v[162:165], v[202:205], v[14:17]
	v_mfma_f32_16x16x32_bf16 v[14:17], v[158:161], v[198:201], v[14:17]
	v_mfma_f32_16x16x32_bf16 v[22:25], v[158:161], v[190:193], v[22:25]
	v_mfma_f32_16x16x32_bf16 v[22:25], v[162:165], v[194:197], v[22:25]
	v_mfma_f32_16x16x32_bf16 v[18:21], v[178:181], v[194:197], v[18:21]
	v_mfma_f32_16x16x32_bf16 v[18:21], v[174:177], v[190:193], v[18:21]
	v_mfma_f32_16x16x32_bf16 v[26:29], v[174:177], v[182:185], v[26:29]
	v_mfma_f32_16x16x32_bf16 v[26:29], v[178:181], v[186:189], v[26:29]
	v_mfma_f32_16x16x32_bf16 v[30:33], v[162:165], v[186:189], v[30:33]
	v_mfma_f32_16x16x32_bf16 v[30:33], v[158:161], v[182:185], v[30:33]
	s_barrier
	s_add_i32 s59, 0, 0x18000
	v_add_u32_e32 v0, s59, v167
	s_add_i32 s62, 0, 0x1c000
	ds_read_b128 v[142:145], v0
	ds_read_b128 v[146:149], v0 offset:1024
	ds_read_b128 v[150:153], v0 offset:2048
	ds_read_b128 v[154:157], v0 offset:3072
	v_add_u32_e32 v0, s62, v167
	ds_read_b128 v[158:161], v0
	ds_read_b128 v[162:165], v0 offset:1024
	ds_read_b128 v[174:177], v0 offset:2048
	ds_read_b128 v[178:181], v0 offset:3072
	s_add_u32 s60, vcc_lo, 0x40000
	s_addc_u32 s61, vcc_hi, 0
	s_mov_b32 m0, s47
	v_lshl_add_u64 v[222:223], s[60:61], 0, v[130:131]
	ds_read_b128 v[182:185], v173 offset:32768
	ds_read_b128 v[186:189], v173 offset:33792
	ds_read_b128 v[190:193], v173 offset:34816
	ds_read_b128 v[194:197], v173 offset:35840
	ds_read_b128 v[198:201], v173 offset:36864
	ds_read_b128 v[202:205], v173 offset:37888
	ds_read_b128 v[206:209], v173 offset:38912
	ds_read_b128 v[210:213], v173 offset:39936
	global_load_lds_dwordx4 v[222:223], off
	v_lshl_add_u64 v[222:223], s[60:61], 0, v[134:135]
	s_mov_b32 m0, s49
	s_nop 0
	global_load_lds_dwordx4 v[222:223], off
	s_waitcnt vmcnt(8)
	s_waitcnt lgkmcnt(0)
	s_barrier
	s_waitcnt lgkmcnt(0)
	v_mfma_f32_16x16x32_bf16 v[126:129], v[142:145], v[182:185], v[126:129]
	v_mfma_f32_16x16x32_bf16 v[126:129], v[146:149], v[186:189], v[126:129]
	v_mfma_f32_16x16x32_bf16 v[122:125], v[154:157], v[186:189], v[122:125]
	v_mfma_f32_16x16x32_bf16 v[122:125], v[150:153], v[182:185], v[122:125]
	v_mfma_f32_16x16x32_bf16 v[114:117], v[150:153], v[190:193], v[114:117]
	v_mfma_f32_16x16x32_bf16 v[114:117], v[154:157], v[194:197], v[114:117]
	v_mfma_f32_16x16x32_bf16 v[118:121], v[146:149], v[194:197], v[118:121]
	v_mfma_f32_16x16x32_bf16 v[118:121], v[142:145], v[190:193], v[118:121]
	v_mfma_f32_16x16x32_bf16 v[110:113], v[142:145], v[198:201], v[110:113]
	v_mfma_f32_16x16x32_bf16 v[110:113], v[146:149], v[202:205], v[110:113]
	v_mfma_f32_16x16x32_bf16 v[106:109], v[154:157], v[202:205], v[106:109]
	v_mfma_f32_16x16x32_bf16 v[106:109], v[150:153], v[198:201], v[106:109]
	v_mfma_f32_16x16x32_bf16 v[98:101], v[150:153], v[206:209], v[98:101]
	v_mfma_f32_16x16x32_bf16 v[98:101], v[154:157], v[210:213], v[98:101]
	v_mfma_f32_16x16x32_bf16 v[102:105], v[146:149], v[210:213], v[102:105]
	v_mfma_f32_16x16x32_bf16 v[102:105], v[142:145], v[206:209], v[102:105]
	v_mfma_f32_16x16x32_bf16 v[38:41], v[158:161], v[206:209], v[38:41]
	v_mfma_f32_16x16x32_bf16 v[38:41], v[162:165], v[210:213], v[38:41]
	v_mfma_f32_16x16x32_bf16 v[34:37], v[178:181], v[210:213], v[34:37]
	v_mfma_f32_16x16x32_bf16 v[34:37], v[174:177], v[206:209], v[34:37]
	v_mfma_f32_16x16x32_bf16 v[46:49], v[174:177], v[198:201], v[46:49]
	v_mfma_f32_16x16x32_bf16 v[46:49], v[178:181], v[202:205], v[46:49]
	v_mfma_f32_16x16x32_bf16 v[54:57], v[162:165], v[202:205], v[54:57]
	v_mfma_f32_16x16x32_bf16 v[54:57], v[158:161], v[198:201], v[54:57]
	v_mfma_f32_16x16x32_bf16 v[70:73], v[158:161], v[190:193], v[70:73]
	v_mfma_f32_16x16x32_bf16 v[70:73], v[162:165], v[194:197], v[70:73]
	v_mfma_f32_16x16x32_bf16 v[62:65], v[178:181], v[194:197], v[62:65]
	v_mfma_f32_16x16x32_bf16 v[62:65], v[174:177], v[190:193], v[62:65]
	v_mfma_f32_16x16x32_bf16 v[74:77], v[174:177], v[182:185], v[74:77]
	v_mfma_f32_16x16x32_bf16 v[74:77], v[178:181], v[186:189], v[74:77]
	v_mfma_f32_16x16x32_bf16 v[82:85], v[162:165], v[186:189], v[82:85]
	v_mfma_f32_16x16x32_bf16 v[82:85], v[158:161], v[182:185], v[82:85]
	s_barrier
	s_add_i32 s59, s59, s44
	v_lshl_add_u64 v[214:215], v[214:215], 0, s[98:99]
	s_mov_b32 m0, s59
	ds_read_b128 v[182:185], v173 offset:49152
	ds_read_b128 v[186:189], v173 offset:50176
	ds_read_b128 v[190:193], v173 offset:51200
	ds_read_b128 v[194:197], v173 offset:52224
	ds_read_b128 v[198:201], v173 offset:53248
	ds_read_b128 v[202:205], v173 offset:54272
	ds_read_b128 v[206:209], v173 offset:55296
	ds_read_b128 v[210:213], v173 offset:56320
	global_load_lds_dwordx4 v[214:215], off
	s_add_i32 m0, s59, 0x2000
	s_add_u32 s26, s26, 0x40080
	v_lshl_add_u64 v[214:215], v[216:217], 0, s[98:99]
	s_addc_u32 s27, s27, 0
	s_add_i32 s59, s62, s44
	global_load_lds_dwordx4 v[214:215], off
	v_lshl_add_u64 v[214:215], s[26:27], 0, v[132:133]
	s_mov_b32 m0, s59
	s_nop 0
	global_load_lds_dwordx4 v[214:215], off
	v_lshl_add_u64 v[214:215], s[26:27], 0, v[136:137]
	s_add_i32 m0, s59, 0x2000
	s_nop 0
	global_load_lds_dwordx4 v[214:215], off
	v_lshl_add_u64 v[214:215], v[218:219], 0, s[98:99]
	s_mov_b32 m0, s52
	s_nop 0
	global_load_lds_dwordx4 v[214:215], off
	v_lshl_add_u64 v[214:215], v[220:221], 0, s[98:99]
	s_mov_b32 m0, s53
	s_nop 0
	global_load_lds_dwordx4 v[214:215], off
	s_waitcnt vmcnt(8)
	s_waitcnt lgkmcnt(0)
	s_barrier
	s_waitcnt lgkmcnt(0)
	v_mfma_f32_16x16x32_bf16 v[94:97], v[142:145], v[182:185], v[94:97]
	v_mfma_f32_16x16x32_bf16 v[94:97], v[146:149], v[186:189], v[94:97]
	v_mfma_f32_16x16x32_bf16 v[90:93], v[154:157], v[186:189], v[90:93]
	v_mfma_f32_16x16x32_bf16 v[90:93], v[150:153], v[182:185], v[90:93]
	v_mfma_f32_16x16x32_bf16 v[78:81], v[150:153], v[190:193], v[78:81]
	v_mfma_f32_16x16x32_bf16 v[78:81], v[154:157], v[194:197], v[78:81]
	v_mfma_f32_16x16x32_bf16 v[86:89], v[146:149], v[194:197], v[86:89]
	v_mfma_f32_16x16x32_bf16 v[86:89], v[142:145], v[190:193], v[86:89]
	v_mfma_f32_16x16x32_bf16 v[66:69], v[142:145], v[198:201], v[66:69]
	v_mfma_f32_16x16x32_bf16 v[66:69], v[146:149], v[202:205], v[66:69]
	v_mfma_f32_16x16x32_bf16 v[58:61], v[154:157], v[202:205], v[58:61]
	v_mfma_f32_16x16x32_bf16 v[58:61], v[150:153], v[198:201], v[58:61]
	v_mfma_f32_16x16x32_bf16 v[42:45], v[150:153], v[206:209], v[42:45]
	v_mfma_f32_16x16x32_bf16 v[42:45], v[154:157], v[210:213], v[42:45]
	v_mfma_f32_16x16x32_bf16 v[50:53], v[146:149], v[210:213], v[50:53]
	v_mfma_f32_16x16x32_bf16 v[50:53], v[142:145], v[206:209], v[50:53]
	v_mfma_f32_16x16x32_bf16 v[6:9], v[158:161], v[206:209], v[6:9]
	v_mfma_f32_16x16x32_bf16 v[6:9], v[162:165], v[210:213], v[6:9]
	v_mfma_f32_16x16x32_bf16 v[2:5], v[178:181], v[210:213], v[2:5]
	v_mfma_f32_16x16x32_bf16 v[2:5], v[174:177], v[206:209], v[2:5]
	v_mfma_f32_16x16x32_bf16 v[10:13], v[174:177], v[198:201], v[10:13]
	v_mfma_f32_16x16x32_bf16 v[10:13], v[178:181], v[202:205], v[10:13]
	v_mfma_f32_16x16x32_bf16 v[14:17], v[162:165], v[202:205], v[14:17]
	v_mfma_f32_16x16x32_bf16 v[14:17], v[158:161], v[198:201], v[14:17]
	v_mfma_f32_16x16x32_bf16 v[22:25], v[158:161], v[190:193], v[22:25]
	v_mfma_f32_16x16x32_bf16 v[22:25], v[162:165], v[194:197], v[22:25]
	v_mfma_f32_16x16x32_bf16 v[18:21], v[178:181], v[194:197], v[18:21]
	v_mfma_f32_16x16x32_bf16 v[18:21], v[174:177], v[190:193], v[18:21]
	v_mfma_f32_16x16x32_bf16 v[26:29], v[174:177], v[182:185], v[26:29]
	v_mfma_f32_16x16x32_bf16 v[26:29], v[178:181], v[186:189], v[26:29]
	v_mfma_f32_16x16x32_bf16 v[30:33], v[162:165], v[186:189], v[30:33]
	v_mfma_f32_16x16x32_bf16 v[30:33], v[158:161], v[182:185], v[30:33]
	s_barrier
	s_add_i32 s58, s58, 2
	s_add_u32 s40, s40, 0x100
	s_addc_u32 s41, s41, 0
	s_add_u32 s56, s56, 0x100
	s_addc_u32 s57, s57, 0
	s_cmp_gt_u32 s58, 13
	s_cbranch_scc0 .LBB0_160

.LBB0_216:
	s_add_i32 s13, s61, -2
	s_add_u32 s28, s28, 0x80
	s_addc_u32 s29, s29, 0
	s_add_u32 s23, s40, 0x100
	s_addc_u32 s40, s41, 0
	s_mov_b32 s30, 0
	s_add_i32 s41, s30, 2
	s_add_u32 vcc_lo, s28, 0x80
	s_addc_u32 s31, s29, 0
	s_add_i32 s62, 0, 0x10000
	s_cmp_eq_u32 s13, s30
	s_cselect_b32 s31, s25, s31
	s_cselect_b32 s30, s24, vcc_lo
	v_add_u32_e32 v145, s62, v175
	s_cselect_b32 vcc_hi, s27, s40
	s_cselect_b32 vcc_lo, s26, s23
	s_add_i32 s63, 0, 0x14000
	ds_read_b128 v[130:133], v145
	ds_read_b128 v[134:137], v145 offset:1024
	ds_read_b128 v[152:155], v145 offset:2048
	ds_read_b128 v[156:159], v145 offset:3072
	v_add_u32_e32 v145, s63, v175
	ds_read_b128 v[160:163], v145
	ds_read_b128 v[164:167], v145 offset:1024
	ds_read_b128 v[168:171], v145 offset:2048
	ds_read_b128 v[186:189], v145 offset:3072
	v_lshl_add_u64 v[172:173], s[28:29], 0, v[148:149]
	s_add_i32 m0, s93, 0xc000
	ds_read_b128 v[190:193], v184
	ds_read_b128 v[194:197], v184 offset:1024
	ds_read_b128 v[198:201], v184 offset:2048
	ds_read_b128 v[202:205], v184 offset:3072
	ds_read_b128 v[206:209], v184 offset:4096
	ds_read_b128 v[210:213], v184 offset:5120
	ds_read_b128 v[214:217], v184 offset:6144
	ds_read_b128 v[218:221], v184 offset:7168
	global_load_lds_dwordx4 v[172:173], off
	v_lshl_add_u64 v[172:173], s[28:29], 0, v[150:151]
	s_add_i32 m0, s93, 0xe000
	s_nop 0
	global_load_lds_dwordx4 v[172:173], off
	s_waitcnt vmcnt(8)
	s_waitcnt lgkmcnt(0)
	s_barrier
	s_waitcnt lgkmcnt(0)
	v_mfma_f32_16x16x32_bf16 v[126:129], v[130:133], v[190:193], 0
	v_mfma_f32_16x16x32_bf16 v[126:129], v[134:137], v[194:197], v[126:129]
	v_mfma_f32_16x16x32_bf16 v[122:125], v[156:159], v[194:197], 0
	v_mfma_f32_16x16x32_bf16 v[122:125], v[152:155], v[190:193], v[122:125]
	v_mfma_f32_16x16x32_bf16 v[106:109], v[152:155], v[198:201], 0
	v_mfma_f32_16x16x32_bf16 v[106:109], v[156:159], v[202:205], v[106:109]
	v_mfma_f32_16x16x32_bf16 v[110:113], v[134:137], v[202:205], 0
	v_mfma_f32_16x16x32_bf16 v[110:113], v[130:133], v[198:201], v[110:113]
	v_mfma_f32_16x16x32_bf16 v[94:97], v[130:133], v[206:209], 0
	v_mfma_f32_16x16x32_bf16 v[94:97], v[134:137], v[210:213], v[94:97]
	v_mfma_f32_16x16x32_bf16 v[90:93], v[156:159], v[210:213], 0
	v_mfma_f32_16x16x32_bf16 v[90:93], v[152:155], v[206:209], v[90:93]
	v_mfma_f32_16x16x32_bf16 v[74:77], v[152:155], v[214:217], 0
	v_mfma_f32_16x16x32_bf16 v[74:77], v[156:159], v[218:221], v[74:77]
	v_mfma_f32_16x16x32_bf16 v[78:81], v[134:137], v[218:221], 0
	v_mfma_f32_16x16x32_bf16 v[78:81], v[130:133], v[214:217], v[78:81]
	v_mfma_f32_16x16x32_bf16 v[70:73], v[160:163], v[214:217], 0
	v_mfma_f32_16x16x32_bf16 v[70:73], v[164:167], v[218:221], v[70:73]
	v_mfma_f32_16x16x32_bf16 v[66:69], v[186:189], v[218:221], 0
	v_mfma_f32_16x16x32_bf16 v[66:69], v[168:171], v[214:217], v[66:69]
	v_mfma_f32_16x16x32_bf16 v[82:85], v[168:171], v[206:209], 0
	v_mfma_f32_16x16x32_bf16 v[82:85], v[186:189], v[210:213], v[82:85]
	v_mfma_f32_16x16x32_bf16 v[86:89], v[164:167], v[210:213], 0
	v_mfma_f32_16x16x32_bf16 v[86:89], v[160:163], v[206:209], v[86:89]
	v_mfma_f32_16x16x32_bf16 v[102:105], v[160:163], v[198:201], 0
	v_mfma_f32_16x16x32_bf16 v[102:105], v[164:167], v[202:205], v[102:105]
	v_mfma_f32_16x16x32_bf16 v[98:101], v[186:189], v[202:205], 0
	v_mfma_f32_16x16x32_bf16 v[98:101], v[168:171], v[198:201], v[98:101]
	v_mfma_f32_16x16x32_bf16 v[114:117], v[168:171], v[190:193], 0
	v_mfma_f32_16x16x32_bf16 v[114:117], v[186:189], v[194:197], v[114:117]
	v_mfma_f32_16x16x32_bf16 v[118:121], v[164:167], v[194:197], 0
	v_mfma_f32_16x16x32_bf16 v[118:121], v[160:163], v[190:193], v[118:121]
	s_barrier
	s_add_i32 s62, s62, s49
	v_lshl_add_u64 v[172:173], vcc, 0, v[0:1]
	s_mov_b32 m0, s62
	ds_read_b128 v[190:193], v184 offset:16384
	ds_read_b128 v[194:197], v184 offset:17408
	ds_read_b128 v[198:201], v184 offset:18432
	ds_read_b128 v[202:205], v184 offset:19456
	ds_read_b128 v[206:209], v184 offset:20480
	ds_read_b128 v[210:213], v184 offset:21504
	ds_read_b128 v[214:217], v184 offset:22528
	ds_read_b128 v[218:221], v184 offset:23552
	global_load_lds_dwordx4 v[172:173], off
	s_add_i32 m0, s62, 0x2000
	v_lshl_add_u64 v[222:223], vcc, 0, v[142:143]
	s_add_u32 vcc_lo, vcc_lo, s96
	s_addc_u32 vcc_hi, vcc_hi, 0
	s_add_i32 s62, s63, s49
	global_load_lds_dwordx4 v[222:223], off
	v_lshl_add_u64 v[236:237], vcc, 0, v[0:1]
	s_mov_b32 m0, s62
	v_lshl_add_u64 v[238:239], vcc, 0, v[142:143]
	global_load_lds_dwordx4 v[236:237], off
	s_add_i32 m0, s62, 0x2000
	v_lshl_add_u64 v[240:241], s[30:31], 0, v[138:139]
	global_load_lds_dwordx4 v[238:239], off
	s_mov_b32 m0, s93
	v_lshl_add_u64 v[242:243], s[30:31], 0, v[140:141]
	global_load_lds_dwordx4 v[240:241], off
	s_mov_b32 m0, s88
	s_nop 0
	global_load_lds_dwordx4 v[242:243], off
	s_waitcnt vmcnt(8)
	s_waitcnt lgkmcnt(0)
	s_barrier
	s_waitcnt lgkmcnt(0)
	v_mfma_f32_16x16x32_bf16 v[62:65], v[130:133], v[190:193], 0
	v_mfma_f32_16x16x32_bf16 v[62:65], v[134:137], v[194:197], v[62:65]
	v_mfma_f32_16x16x32_bf16 v[58:61], v[156:159], v[194:197], 0
	v_mfma_f32_16x16x32_bf16 v[58:61], v[152:155], v[190:193], v[58:61]
	v_mfma_f32_16x16x32_bf16 v[42:45], v[152:155], v[198:201], 0
	v_mfma_f32_16x16x32_bf16 v[42:45], v[156:159], v[202:205], v[42:45]
	v_mfma_f32_16x16x32_bf16 v[46:49], v[134:137], v[202:205], 0
	v_mfma_f32_16x16x32_bf16 v[46:49], v[130:133], v[198:201], v[46:49]
	v_mfma_f32_16x16x32_bf16 v[30:33], v[130:133], v[206:209], 0
	v_mfma_f32_16x16x32_bf16 v[30:33], v[134:137], v[210:213], v[30:33]
	v_mfma_f32_16x16x32_bf16 v[26:29], v[156:159], v[210:213], 0
	v_mfma_f32_16x16x32_bf16 v[26:29], v[152:155], v[206:209], v[26:29]
	v_mfma_f32_16x16x32_bf16 v[10:13], v[152:155], v[214:217], 0
	v_mfma_f32_16x16x32_bf16 v[10:13], v[156:159], v[218:221], v[10:13]
	v_mfma_f32_16x16x32_bf16 v[14:17], v[134:137], v[218:221], 0
	v_mfma_f32_16x16x32_bf16 v[14:17], v[130:133], v[214:217], v[14:17]
	v_mfma_f32_16x16x32_bf16 v[6:9], v[160:163], v[214:217], 0
	v_mfma_f32_16x16x32_bf16 v[6:9], v[164:167], v[218:221], v[6:9]
	v_mfma_f32_16x16x32_bf16 v[2:5], v[186:189], v[218:221], 0
	v_mfma_f32_16x16x32_bf16 v[2:5], v[168:171], v[214:217], v[2:5]
	v_mfma_f32_16x16x32_bf16 v[18:21], v[168:171], v[206:209], 0
	v_mfma_f32_16x16x32_bf16 v[18:21], v[186:189], v[210:213], v[18:21]
	v_mfma_f32_16x16x32_bf16 v[22:25], v[164:167], v[210:213], 0
	v_mfma_f32_16x16x32_bf16 v[22:25], v[160:163], v[206:209], v[22:25]
	v_mfma_f32_16x16x32_bf16 v[38:41], v[160:163], v[198:201], 0
	v_mfma_f32_16x16x32_bf16 v[38:41], v[164:167], v[202:205], v[38:41]
	v_mfma_f32_16x16x32_bf16 v[34:37], v[186:189], v[202:205], 0
	v_mfma_f32_16x16x32_bf16 v[34:37], v[168:171], v[198:201], v[34:37]
	v_mfma_f32_16x16x32_bf16 v[50:53], v[168:171], v[190:193], 0
	v_mfma_f32_16x16x32_bf16 v[50:53], v[186:189], v[194:197], v[50:53]
	v_mfma_f32_16x16x32_bf16 v[54:57], v[164:167], v[194:197], 0
	v_mfma_f32_16x16x32_bf16 v[54:57], v[160:163], v[190:193], v[54:57]
	s_barrier
	s_add_i32 s62, 0, 0x18000
	v_add_u32_e32 v145, s62, v175
	s_add_i32 s63, 0, 0x1c000
	ds_read_b128 v[130:133], v145
	ds_read_b128 v[134:137], v145 offset:1024
	ds_read_b128 v[152:155], v145 offset:2048
	ds_read_b128 v[156:159], v145 offset:3072
	v_add_u32_e32 v145, s63, v175
	ds_read_b128 v[160:163], v145
	ds_read_b128 v[164:167], v145 offset:1024
	ds_read_b128 v[168:171], v145 offset:2048
	ds_read_b128 v[186:189], v145 offset:3072
	s_add_u32 s30, s30, s96
	s_addc_u32 s31, s31, 0
	s_mov_b32 m0, s89
	v_lshl_add_u64 v[244:245], s[30:31], 0, v[138:139]
	ds_read_b128 v[190:193], v184 offset:32768
	ds_read_b128 v[194:197], v184 offset:33792
	ds_read_b128 v[198:201], v184 offset:34816
	ds_read_b128 v[202:205], v184 offset:35840
	ds_read_b128 v[206:209], v184 offset:36864
	ds_read_b128 v[210:213], v184 offset:37888
	ds_read_b128 v[214:217], v184 offset:38912
	ds_read_b128 v[218:221], v184 offset:39936
	global_load_lds_dwordx4 v[244:245], off
	v_lshl_add_u64 v[244:245], s[30:31], 0, v[140:141]
	s_mov_b32 m0, s52
	s_nop 0
	global_load_lds_dwordx4 v[244:245], off
	s_waitcnt vmcnt(8)
	s_waitcnt lgkmcnt(0)
	s_barrier
	s_waitcnt lgkmcnt(0)
	v_mfma_f32_16x16x32_bf16 v[126:129], v[130:133], v[190:193], v[126:129]
	v_mfma_f32_16x16x32_bf16 v[126:129], v[134:137], v[194:197], v[126:129]
	v_mfma_f32_16x16x32_bf16 v[122:125], v[156:159], v[194:197], v[122:125]
	v_mfma_f32_16x16x32_bf16 v[122:125], v[152:155], v[190:193], v[122:125]
	v_mfma_f32_16x16x32_bf16 v[106:109], v[152:155], v[198:201], v[106:109]
	v_mfma_f32_16x16x32_bf16 v[106:109], v[156:159], v[202:205], v[106:109]
	v_mfma_f32_16x16x32_bf16 v[110:113], v[134:137], v[202:205], v[110:113]
	v_mfma_f32_16x16x32_bf16 v[110:113], v[130:133], v[198:201], v[110:113]
	v_mfma_f32_16x16x32_bf16 v[94:97], v[130:133], v[206:209], v[94:97]
	v_mfma_f32_16x16x32_bf16 v[94:97], v[134:137], v[210:213], v[94:97]
	v_mfma_f32_16x16x32_bf16 v[90:93], v[156:159], v[210:213], v[90:93]
	v_mfma_f32_16x16x32_bf16 v[90:93], v[152:155], v[206:209], v[90:93]
	v_mfma_f32_16x16x32_bf16 v[74:77], v[152:155], v[214:217], v[74:77]
	v_mfma_f32_16x16x32_bf16 v[74:77], v[156:159], v[218:221], v[74:77]
	v_mfma_f32_16x16x32_bf16 v[78:81], v[134:137], v[218:221], v[78:81]
	v_mfma_f32_16x16x32_bf16 v[78:81], v[130:133], v[214:217], v[78:81]
	v_mfma_f32_16x16x32_bf16 v[70:73], v[160:163], v[214:217], v[70:73]
	v_mfma_f32_16x16x32_bf16 v[70:73], v[164:167], v[218:221], v[70:73]
	v_mfma_f32_16x16x32_bf16 v[66:69], v[186:189], v[218:221], v[66:69]
	v_mfma_f32_16x16x32_bf16 v[66:69], v[168:171], v[214:217], v[66:69]
	v_mfma_f32_16x16x32_bf16 v[82:85], v[168:171], v[206:209], v[82:85]
	v_mfma_f32_16x16x32_bf16 v[82:85], v[186:189], v[210:213], v[82:85]
	v_mfma_f32_16x16x32_bf16 v[86:89], v[164:167], v[210:213], v[86:89]
	v_mfma_f32_16x16x32_bf16 v[86:89], v[160:163], v[206:209], v[86:89]
	v_mfma_f32_16x16x32_bf16 v[102:105], v[160:163], v[198:201], v[102:105]
	v_mfma_f32_16x16x32_bf16 v[102:105], v[164:167], v[202:205], v[102:105]
	v_mfma_f32_16x16x32_bf16 v[98:101], v[186:189], v[202:205], v[98:101]
	v_mfma_f32_16x16x32_bf16 v[98:101], v[168:171], v[198:201], v[98:101]
	v_mfma_f32_16x16x32_bf16 v[114:117], v[168:171], v[190:193], v[114:117]
	v_mfma_f32_16x16x32_bf16 v[114:117], v[186:189], v[194:197], v[114:117]
	v_mfma_f32_16x16x32_bf16 v[118:121], v[164:167], v[194:197], v[118:121]
	v_mfma_f32_16x16x32_bf16 v[118:121], v[160:163], v[190:193], v[118:121]
	s_barrier
	s_add_i32 s30, s62, s49
	v_lshl_add_u64 v[172:173], v[172:173], 0, s[98:99]
	s_mov_b32 m0, s30
	ds_read_b128 v[190:193], v184 offset:49152
	ds_read_b128 v[194:197], v184 offset:50176
	ds_read_b128 v[198:201], v184 offset:51200
	ds_read_b128 v[202:205], v184 offset:52224
	ds_read_b128 v[206:209], v184 offset:53248
	ds_read_b128 v[210:213], v184 offset:54272
	ds_read_b128 v[214:217], v184 offset:55296
	ds_read_b128 v[218:221], v184 offset:56320
	global_load_lds_dwordx4 v[172:173], off
	v_lshl_add_u64 v[172:173], v[222:223], 0, s[98:99]
	s_add_i32 m0, s30, 0x2000
	s_add_i32 s30, s63, s49
	global_load_lds_dwordx4 v[172:173], off
	v_lshl_add_u64 v[172:173], v[236:237], 0, s[98:99]
	s_mov_b32 m0, s30
	s_nop 0
	global_load_lds_dwordx4 v[172:173], off
	v_lshl_add_u64 v[172:173], v[238:239], 0, s[98:99]
	s_add_i32 m0, s30, 0x2000
	s_nop 0
	global_load_lds_dwordx4 v[172:173], off
	v_lshl_add_u64 v[172:173], v[240:241], 0, s[98:99]
	s_mov_b32 m0, s95
	s_nop 0
	global_load_lds_dwordx4 v[172:173], off
	v_lshl_add_u64 v[172:173], v[242:243], 0, s[98:99]
	s_mov_b32 m0, s54
	s_nop 0
	global_load_lds_dwordx4 v[172:173], off
	s_waitcnt vmcnt(8)
	s_waitcnt lgkmcnt(0)
	s_barrier
	s_waitcnt lgkmcnt(0)
	v_mfma_f32_16x16x32_bf16 v[62:65], v[130:133], v[190:193], v[62:65]
	v_mfma_f32_16x16x32_bf16 v[62:65], v[134:137], v[194:197], v[62:65]
	v_mfma_f32_16x16x32_bf16 v[58:61], v[156:159], v[194:197], v[58:61]
	v_mfma_f32_16x16x32_bf16 v[58:61], v[152:155], v[190:193], v[58:61]
	v_mfma_f32_16x16x32_bf16 v[42:45], v[152:155], v[198:201], v[42:45]
	v_mfma_f32_16x16x32_bf16 v[42:45], v[156:159], v[202:205], v[42:45]
	v_mfma_f32_16x16x32_bf16 v[46:49], v[134:137], v[202:205], v[46:49]
	v_mfma_f32_16x16x32_bf16 v[46:49], v[130:133], v[198:201], v[46:49]
	v_mfma_f32_16x16x32_bf16 v[30:33], v[130:133], v[206:209], v[30:33]
	v_mfma_f32_16x16x32_bf16 v[30:33], v[134:137], v[210:213], v[30:33]
	v_mfma_f32_16x16x32_bf16 v[26:29], v[156:159], v[210:213], v[26:29]
	v_mfma_f32_16x16x32_bf16 v[26:29], v[152:155], v[206:209], v[26:29]
	v_mfma_f32_16x16x32_bf16 v[10:13], v[152:155], v[214:217], v[10:13]
	v_mfma_f32_16x16x32_bf16 v[10:13], v[156:159], v[218:221], v[10:13]
	v_mfma_f32_16x16x32_bf16 v[14:17], v[134:137], v[218:221], v[14:17]
	v_mfma_f32_16x16x32_bf16 v[14:17], v[130:133], v[214:217], v[14:17]
	v_mfma_f32_16x16x32_bf16 v[6:9], v[160:163], v[214:217], v[6:9]
	v_mfma_f32_16x16x32_bf16 v[6:9], v[164:167], v[218:221], v[6:9]
	v_mfma_f32_16x16x32_bf16 v[2:5], v[186:189], v[218:221], v[2:5]
	v_mfma_f32_16x16x32_bf16 v[2:5], v[168:171], v[214:217], v[2:5]
	v_mfma_f32_16x16x32_bf16 v[18:21], v[168:171], v[206:209], v[18:21]
	v_mfma_f32_16x16x32_bf16 v[18:21], v[186:189], v[210:213], v[18:21]
	v_mfma_f32_16x16x32_bf16 v[22:25], v[164:167], v[210:213], v[22:25]
	v_mfma_f32_16x16x32_bf16 v[22:25], v[160:163], v[206:209], v[22:25]
	v_mfma_f32_16x16x32_bf16 v[38:41], v[160:163], v[198:201], v[38:41]
	v_mfma_f32_16x16x32_bf16 v[38:41], v[164:167], v[202:205], v[38:41]
	v_mfma_f32_16x16x32_bf16 v[34:37], v[186:189], v[202:205], v[34:37]
	v_mfma_f32_16x16x32_bf16 v[34:37], v[168:171], v[198:201], v[34:37]
	v_mfma_f32_16x16x32_bf16 v[50:53], v[168:171], v[190:193], v[50:53]
	v_mfma_f32_16x16x32_bf16 v[50:53], v[186:189], v[194:197], v[50:53]
	v_mfma_f32_16x16x32_bf16 v[54:57], v[164:167], v[194:197], v[54:57]
	v_mfma_f32_16x16x32_bf16 v[54:57], v[160:163], v[190:193], v[54:57]
	s_barrier
	s_add_u32 s28, s28, 0x100
	s_addc_u32 s29, s29, 0
	s_add_u32 s23, s23, 0x100
	s_addc_u32 s40, s40, 0
	s_cmp_ge_i32 s41, s61
	s_mov_b32 s30, s41
	s_cbranch_scc1 .Lpeel_done_217
.LBB0_217:
	s_add_i32 s41, s30, 2
	s_add_u32 vcc_lo, s28, 0x80
	s_addc_u32 s31, s29, 0
	s_add_i32 s62, 0, 0x10000
	s_cmp_eq_u32 s13, s30
	s_cselect_b32 s31, s25, s31
	s_cselect_b32 s30, s24, vcc_lo
	v_add_u32_e32 v145, s62, v175
	s_cselect_b32 vcc_hi, s27, s40
	s_cselect_b32 vcc_lo, s26, s23
	s_add_i32 s63, 0, 0x14000
	ds_read_b128 v[130:133], v145
	ds_read_b128 v[134:137], v145 offset:1024
	ds_read_b128 v[152:155], v145 offset:2048
	ds_read_b128 v[156:159], v145 offset:3072
	v_add_u32_e32 v145, s63, v175
	ds_read_b128 v[160:163], v145
	ds_read_b128 v[164:167], v145 offset:1024
	ds_read_b128 v[168:171], v145 offset:2048
	ds_read_b128 v[186:189], v145 offset:3072
	v_lshl_add_u64 v[172:173], s[28:29], 0, v[148:149]
	s_add_i32 m0, s93, 0xc000
	ds_read_b128 v[190:193], v184
	ds_read_b128 v[194:197], v184 offset:1024
	ds_read_b128 v[198:201], v184 offset:2048
	ds_read_b128 v[202:205], v184 offset:3072
	ds_read_b128 v[206:209], v184 offset:4096
	ds_read_b128 v[210:213], v184 offset:5120
	ds_read_b128 v[214:217], v184 offset:6144
	ds_read_b128 v[218:221], v184 offset:7168
	global_load_lds_dwordx4 v[172:173], off
	v_lshl_add_u64 v[172:173], s[28:29], 0, v[150:151]
	s_add_i32 m0, s93, 0xe000
	s_nop 0
	global_load_lds_dwordx4 v[172:173], off
	s_waitcnt vmcnt(8)
	s_waitcnt lgkmcnt(0)
	s_barrier
	s_waitcnt lgkmcnt(0)
	v_mfma_f32_16x16x32_bf16 v[126:129], v[130:133], v[190:193], v[126:129]
	v_mfma_f32_16x16x32_bf16 v[126:129], v[134:137], v[194:197], v[126:129]
	v_mfma_f32_16x16x32_bf16 v[122:125], v[156:159], v[194:197], v[122:125]
	v_mfma_f32_16x16x32_bf16 v[122:125], v[152:155], v[190:193], v[122:125]
	v_mfma_f32_16x16x32_bf16 v[106:109], v[152:155], v[198:201], v[106:109]
	v_mfma_f32_16x16x32_bf16 v[106:109], v[156:159], v[202:205], v[106:109]
	v_mfma_f32_16x16x32_bf16 v[110:113], v[134:137], v[202:205], v[110:113]
	v_mfma_f32_16x16x32_bf16 v[110:113], v[130:133], v[198:201], v[110:113]
	v_mfma_f32_16x16x32_bf16 v[94:97], v[130:133], v[206:209], v[94:97]
	v_mfma_f32_16x16x32_bf16 v[94:97], v[134:137], v[210:213], v[94:97]
	v_mfma_f32_16x16x32_bf16 v[90:93], v[156:159], v[210:213], v[90:93]
	v_mfma_f32_16x16x32_bf16 v[90:93], v[152:155], v[206:209], v[90:93]
	v_mfma_f32_16x16x32_bf16 v[74:77], v[152:155], v[214:217], v[74:77]
	v_mfma_f32_16x16x32_bf16 v[74:77], v[156:159], v[218:221], v[74:77]
	v_mfma_f32_16x16x32_bf16 v[78:81], v[134:137], v[218:221], v[78:81]
	v_mfma_f32_16x16x32_bf16 v[78:81], v[130:133], v[214:217], v[78:81]
	v_mfma_f32_16x16x32_bf16 v[70:73], v[160:163], v[214:217], v[70:73]
	v_mfma_f32_16x16x32_bf16 v[70:73], v[164:167], v[218:221], v[70:73]
	v_mfma_f32_16x16x32_bf16 v[66:69], v[186:189], v[218:221], v[66:69]
	v_mfma_f32_16x16x32_bf16 v[66:69], v[168:171], v[214:217], v[66:69]
	v_mfma_f32_16x16x32_bf16 v[82:85], v[168:171], v[206:209], v[82:85]
	v_mfma_f32_16x16x32_bf16 v[82:85], v[186:189], v[210:213], v[82:85]
	v_mfma_f32_16x16x32_bf16 v[86:89], v[164:167], v[210:213], v[86:89]
	v_mfma_f32_16x16x32_bf16 v[86:89], v[160:163], v[206:209], v[86:89]
	v_mfma_f32_16x16x32_bf16 v[102:105], v[160:163], v[198:201], v[102:105]
	v_mfma_f32_16x16x32_bf16 v[102:105], v[164:167], v[202:205], v[102:105]
	v_mfma_f32_16x16x32_bf16 v[98:101], v[186:189], v[202:205], v[98:101]
	v_mfma_f32_16x16x32_bf16 v[98:101], v[168:171], v[198:201], v[98:101]
	v_mfma_f32_16x16x32_bf16 v[114:117], v[168:171], v[190:193], v[114:117]
	v_mfma_f32_16x16x32_bf16 v[114:117], v[186:189], v[194:197], v[114:117]
	v_mfma_f32_16x16x32_bf16 v[118:121], v[164:167], v[194:197], v[118:121]
	v_mfma_f32_16x16x32_bf16 v[118:121], v[160:163], v[190:193], v[118:121]
	s_barrier
	s_add_i32 s62, s62, s49
	v_lshl_add_u64 v[172:173], vcc, 0, v[0:1]
	s_mov_b32 m0, s62
	ds_read_b128 v[190:193], v184 offset:16384
	ds_read_b128 v[194:197], v184 offset:17408
	ds_read_b128 v[198:201], v184 offset:18432
	ds_read_b128 v[202:205], v184 offset:19456
	ds_read_b128 v[206:209], v184 offset:20480
	ds_read_b128 v[210:213], v184 offset:21504
	ds_read_b128 v[214:217], v184 offset:22528
	ds_read_b128 v[218:221], v184 offset:23552
	global_load_lds_dwordx4 v[172:173], off
	s_add_i32 m0, s62, 0x2000
	v_lshl_add_u64 v[222:223], vcc, 0, v[142:143]
	s_add_u32 vcc_lo, vcc_lo, s96
	s_addc_u32 vcc_hi, vcc_hi, 0
	s_add_i32 s62, s63, s49
	global_load_lds_dwordx4 v[222:223], off
	v_lshl_add_u64 v[236:237], vcc, 0, v[0:1]
	s_mov_b32 m0, s62
	v_lshl_add_u64 v[238:239], vcc, 0, v[142:143]
	global_load_lds_dwordx4 v[236:237], off
	s_add_i32 m0, s62, 0x2000
	v_lshl_add_u64 v[240:241], s[30:31], 0, v[138:139]
	global_load_lds_dwordx4 v[238:239], off
	s_mov_b32 m0, s93
	v_lshl_add_u64 v[242:243], s[30:31], 0, v[140:141]
	global_load_lds_dwordx4 v[240:241], off
	s_mov_b32 m0, s88
	s_nop 0
	global_load_lds_dwordx4 v[242:243], off
	s_waitcnt vmcnt(8)
	s_waitcnt lgkmcnt(0)
	s_barrier
	s_waitcnt lgkmcnt(0)
	v_mfma_f32_16x16x32_bf16 v[62:65], v[130:133], v[190:193], v[62:65]
	v_mfma_f32_16x16x32_bf16 v[62:65], v[134:137], v[194:197], v[62:65]
	v_mfma_f32_16x16x32_bf16 v[58:61], v[156:159], v[194:197], v[58:61]
	v_mfma_f32_16x16x32_bf16 v[58:61], v[152:155], v[190:193], v[58:61]
	v_mfma_f32_16x16x32_bf16 v[42:45], v[152:155], v[198:201], v[42:45]
	v_mfma_f32_16x16x32_bf16 v[42:45], v[156:159], v[202:205], v[42:45]
	v_mfma_f32_16x16x32_bf16 v[46:49], v[134:137], v[202:205], v[46:49]
	v_mfma_f32_16x16x32_bf16 v[46:49], v[130:133], v[198:201], v[46:49]
	v_mfma_f32_16x16x32_bf16 v[30:33], v[130:133], v[206:209], v[30:33]
	v_mfma_f32_16x16x32_bf16 v[30:33], v[134:137], v[210:213], v[30:33]
	v_mfma_f32_16x16x32_bf16 v[26:29], v[156:159], v[210:213], v[26:29]
	v_mfma_f32_16x16x32_bf16 v[26:29], v[152:155], v[206:209], v[26:29]
	v_mfma_f32_16x16x32_bf16 v[10:13], v[152:155], v[214:217], v[10:13]
	v_mfma_f32_16x16x32_bf16 v[10:13], v[156:159], v[218:221], v[10:13]
	v_mfma_f32_16x16x32_bf16 v[14:17], v[134:137], v[218:221], v[14:17]
	v_mfma_f32_16x16x32_bf16 v[14:17], v[130:133], v[214:217], v[14:17]
	v_mfma_f32_16x16x32_bf16 v[6:9], v[160:163], v[214:217], v[6:9]
	v_mfma_f32_16x16x32_bf16 v[6:9], v[164:167], v[218:221], v[6:9]
	v_mfma_f32_16x16x32_bf16 v[2:5], v[186:189], v[218:221], v[2:5]
	v_mfma_f32_16x16x32_bf16 v[2:5], v[168:171], v[214:217], v[2:5]
	v_mfma_f32_16x16x32_bf16 v[18:21], v[168:171], v[206:209], v[18:21]
	v_mfma_f32_16x16x32_bf16 v[18:21], v[186:189], v[210:213], v[18:21]
	v_mfma_f32_16x16x32_bf16 v[22:25], v[164:167], v[210:213], v[22:25]
	v_mfma_f32_16x16x32_bf16 v[22:25], v[160:163], v[206:209], v[22:25]
	v_mfma_f32_16x16x32_bf16 v[38:41], v[160:163], v[198:201], v[38:41]
	v_mfma_f32_16x16x32_bf16 v[38:41], v[164:167], v[202:205], v[38:41]
	v_mfma_f32_16x16x32_bf16 v[34:37], v[186:189], v[202:205], v[34:37]
	v_mfma_f32_16x16x32_bf16 v[34:37], v[168:171], v[198:201], v[34:37]
	v_mfma_f32_16x16x32_bf16 v[50:53], v[168:171], v[190:193], v[50:53]
	v_mfma_f32_16x16x32_bf16 v[50:53], v[186:189], v[194:197], v[50:53]
	v_mfma_f32_16x16x32_bf16 v[54:57], v[164:167], v[194:197], v[54:57]
	v_mfma_f32_16x16x32_bf16 v[54:57], v[160:163], v[190:193], v[54:57]
	s_barrier
	s_add_i32 s62, 0, 0x18000
	v_add_u32_e32 v145, s62, v175
	s_add_i32 s63, 0, 0x1c000
	ds_read_b128 v[130:133], v145
	ds_read_b128 v[134:137], v145 offset:1024
	ds_read_b128 v[152:155], v145 offset:2048
	ds_read_b128 v[156:159], v145 offset:3072
	v_add_u32_e32 v145, s63, v175
	ds_read_b128 v[160:163], v145
	ds_read_b128 v[164:167], v145 offset:1024
	ds_read_b128 v[168:171], v145 offset:2048
	ds_read_b128 v[186:189], v145 offset:3072
	s_add_u32 s30, s30, s96
	s_addc_u32 s31, s31, 0
	s_mov_b32 m0, s89
	v_lshl_add_u64 v[244:245], s[30:31], 0, v[138:139]
	ds_read_b128 v[190:193], v184 offset:32768
	ds_read_b128 v[194:197], v184 offset:33792
	ds_read_b128 v[198:201], v184 offset:34816
	ds_read_b128 v[202:205], v184 offset:35840
	ds_read_b128 v[206:209], v184 offset:36864
	ds_read_b128 v[210:213], v184 offset:37888
	ds_read_b128 v[214:217], v184 offset:38912
	ds_read_b128 v[218:221], v184 offset:39936
	global_load_lds_dwordx4 v[244:245], off
	v_lshl_add_u64 v[244:245], s[30:31], 0, v[140:141]
	s_mov_b32 m0, s52
	s_nop 0
	global_load_lds_dwordx4 v[244:245], off
	s_waitcnt vmcnt(8)
	s_waitcnt lgkmcnt(0)
	s_barrier
	s_waitcnt lgkmcnt(0)
	v_mfma_f32_16x16x32_bf16 v[126:129], v[130:133], v[190:193], v[126:129]
	v_mfma_f32_16x16x32_bf16 v[126:129], v[134:137], v[194:197], v[126:129]
	v_mfma_f32_16x16x32_bf16 v[122:125], v[156:159], v[194:197], v[122:125]
	v_mfma_f32_16x16x32_bf16 v[122:125], v[152:155], v[190:193], v[122:125]
	v_mfma_f32_16x16x32_bf16 v[106:109], v[152:155], v[198:201], v[106:109]
	v_mfma_f32_16x16x32_bf16 v[106:109], v[156:159], v[202:205], v[106:109]
	v_mfma_f32_16x16x32_bf16 v[110:113], v[134:137], v[202:205], v[110:113]
	v_mfma_f32_16x16x32_bf16 v[110:113], v[130:133], v[198:201], v[110:113]
	v_mfma_f32_16x16x32_bf16 v[94:97], v[130:133], v[206:209], v[94:97]
	v_mfma_f32_16x16x32_bf16 v[94:97], v[134:137], v[210:213], v[94:97]
	v_mfma_f32_16x16x32_bf16 v[90:93], v[156:159], v[210:213], v[90:93]
	v_mfma_f32_16x16x32_bf16 v[90:93], v[152:155], v[206:209], v[90:93]
	v_mfma_f32_16x16x32_bf16 v[74:77], v[152:155], v[214:217], v[74:77]
	v_mfma_f32_16x16x32_bf16 v[74:77], v[156:159], v[218:221], v[74:77]
	v_mfma_f32_16x16x32_bf16 v[78:81], v[134:137], v[218:221], v[78:81]
	v_mfma_f32_16x16x32_bf16 v[78:81], v[130:133], v[214:217], v[78:81]
	v_mfma_f32_16x16x32_bf16 v[70:73], v[160:163], v[214:217], v[70:73]
	v_mfma_f32_16x16x32_bf16 v[70:73], v[164:167], v[218:221], v[70:73]
	v_mfma_f32_16x16x32_bf16 v[66:69], v[186:189], v[218:221], v[66:69]
	v_mfma_f32_16x16x32_bf16 v[66:69], v[168:171], v[214:217], v[66:69]
	v_mfma_f32_16x16x32_bf16 v[82:85], v[168:171], v[206:209], v[82:85]
	v_mfma_f32_16x16x32_bf16 v[82:85], v[186:189], v[210:213], v[82:85]
	v_mfma_f32_16x16x32_bf16 v[86:89], v[164:167], v[210:213], v[86:89]
	v_mfma_f32_16x16x32_bf16 v[86:89], v[160:163], v[206:209], v[86:89]
	v_mfma_f32_16x16x32_bf16 v[102:105], v[160:163], v[198:201], v[102:105]
	v_mfma_f32_16x16x32_bf16 v[102:105], v[164:167], v[202:205], v[102:105]
	v_mfma_f32_16x16x32_bf16 v[98:101], v[186:189], v[202:205], v[98:101]
	v_mfma_f32_16x16x32_bf16 v[98:101], v[168:171], v[198:201], v[98:101]
	v_mfma_f32_16x16x32_bf16 v[114:117], v[168:171], v[190:193], v[114:117]
	v_mfma_f32_16x16x32_bf16 v[114:117], v[186:189], v[194:197], v[114:117]
	v_mfma_f32_16x16x32_bf16 v[118:121], v[164:167], v[194:197], v[118:121]
	v_mfma_f32_16x16x32_bf16 v[118:121], v[160:163], v[190:193], v[118:121]
	s_barrier
	s_add_i32 s30, s62, s49
	v_lshl_add_u64 v[172:173], v[172:173], 0, s[98:99]
	s_mov_b32 m0, s30
	ds_read_b128 v[190:193], v184 offset:49152
	ds_read_b128 v[194:197], v184 offset:50176
	ds_read_b128 v[198:201], v184 offset:51200
	ds_read_b128 v[202:205], v184 offset:52224
	ds_read_b128 v[206:209], v184 offset:53248
	ds_read_b128 v[210:213], v184 offset:54272
	ds_read_b128 v[214:217], v184 offset:55296
	ds_read_b128 v[218:221], v184 offset:56320
	global_load_lds_dwordx4 v[172:173], off
	v_lshl_add_u64 v[172:173], v[222:223], 0, s[98:99]
	s_add_i32 m0, s30, 0x2000
	s_add_i32 s30, s63, s49
	global_load_lds_dwordx4 v[172:173], off
	v_lshl_add_u64 v[172:173], v[236:237], 0, s[98:99]
	s_mov_b32 m0, s30
	s_nop 0
	global_load_lds_dwordx4 v[172:173], off
	v_lshl_add_u64 v[172:173], v[238:239], 0, s[98:99]
	s_add_i32 m0, s30, 0x2000
	s_nop 0
	global_load_lds_dwordx4 v[172:173], off
	v_lshl_add_u64 v[172:173], v[240:241], 0, s[98:99]
	s_mov_b32 m0, s95
	s_nop 0
	global_load_lds_dwordx4 v[172:173], off
	v_lshl_add_u64 v[172:173], v[242:243], 0, s[98:99]
	s_mov_b32 m0, s54
	s_nop 0
	global_load_lds_dwordx4 v[172:173], off
	s_waitcnt vmcnt(8)
	s_waitcnt lgkmcnt(0)
	s_barrier
	s_waitcnt lgkmcnt(0)
	v_mfma_f32_16x16x32_bf16 v[62:65], v[130:133], v[190:193], v[62:65]
	v_mfma_f32_16x16x32_bf16 v[62:65], v[134:137], v[194:197], v[62:65]
	v_mfma_f32_16x16x32_bf16 v[58:61], v[156:159], v[194:197], v[58:61]
	v_mfma_f32_16x16x32_bf16 v[58:61], v[152:155], v[190:193], v[58:61]
	v_mfma_f32_16x16x32_bf16 v[42:45], v[152:155], v[198:201], v[42:45]
	v_mfma_f32_16x16x32_bf16 v[42:45], v[156:159], v[202:205], v[42:45]
	v_mfma_f32_16x16x32_bf16 v[46:49], v[134:137], v[202:205], v[46:49]
	v_mfma_f32_16x16x32_bf16 v[46:49], v[130:133], v[198:201], v[46:49]
	v_mfma_f32_16x16x32_bf16 v[30:33], v[130:133], v[206:209], v[30:33]
	v_mfma_f32_16x16x32_bf16 v[30:33], v[134:137], v[210:213], v[30:33]
	v_mfma_f32_16x16x32_bf16 v[26:29], v[156:159], v[210:213], v[26:29]
	v_mfma_f32_16x16x32_bf16 v[26:29], v[152:155], v[206:209], v[26:29]
	v_mfma_f32_16x16x32_bf16 v[10:13], v[152:155], v[214:217], v[10:13]
	v_mfma_f32_16x16x32_bf16 v[10:13], v[156:159], v[218:221], v[10:13]
	v_mfma_f32_16x16x32_bf16 v[14:17], v[134:137], v[218:221], v[14:17]
	v_mfma_f32_16x16x32_bf16 v[14:17], v[130:133], v[214:217], v[14:17]
	v_mfma_f32_16x16x32_bf16 v[6:9], v[160:163], v[214:217], v[6:9]
	v_mfma_f32_16x16x32_bf16 v[6:9], v[164:167], v[218:221], v[6:9]
	v_mfma_f32_16x16x32_bf16 v[2:5], v[186:189], v[218:221], v[2:5]
	v_mfma_f32_16x16x32_bf16 v[2:5], v[168:171], v[214:217], v[2:5]
	v_mfma_f32_16x16x32_bf16 v[18:21], v[168:171], v[206:209], v[18:21]
	v_mfma_f32_16x16x32_bf16 v[18:21], v[186:189], v[210:213], v[18:21]
	v_mfma_f32_16x16x32_bf16 v[22:25], v[164:167], v[210:213], v[22:25]
	v_mfma_f32_16x16x32_bf16 v[22:25], v[160:163], v[206:209], v[22:25]
	v_mfma_f32_16x16x32_bf16 v[38:41], v[160:163], v[198:201], v[38:41]
	v_mfma_f32_16x16x32_bf16 v[38:41], v[164:167], v[202:205], v[38:41]
	v_mfma_f32_16x16x32_bf16 v[34:37], v[186:189], v[202:205], v[34:37]
	v_mfma_f32_16x16x32_bf16 v[34:37], v[168:171], v[198:201], v[34:37]
	v_mfma_f32_16x16x32_bf16 v[50:53], v[168:171], v[190:193], v[50:53]
	v_mfma_f32_16x16x32_bf16 v[50:53], v[186:189], v[194:197], v[50:53]
	v_mfma_f32_16x16x32_bf16 v[54:57], v[164:167], v[194:197], v[54:57]
	v_mfma_f32_16x16x32_bf16 v[54:57], v[160:163], v[190:193], v[54:57]
	s_barrier
	s_add_u32 s28, s28, 0x100
	s_addc_u32 s29, s29, 0
	s_add_u32 s23, s23, 0x100
	s_addc_u32 s40, s40, 0
	s_cmp_ge_i32 s41, s61
	s_mov_b32 s30, s41
	s_cbranch_scc0 .LBB0_217

.LBB0_373:
	s_ashr_i32 s17, s16, 31
	s_lshl_b64 s[20:21], s[16:17], 19
	s_add_u32 s20, s37, s20
	s_addc_u32 s21, s40, s21
	s_and_b64 s[22:23], s[18:19], exec
	s_cselect_b32 s17, s21, s29
	s_cselect_b32 s25, s20, s28
	s_ashr_i32 s15, s14, 31
	s_lshl_b64 s[22:23], s[14:15], 19
	s_add_u32 s22, s41, s22
	s_addc_u32 s23, s42, s23
	s_and_b64 s[38:39], s[18:19], exec
	s_cselect_b32 s15, s23, s31
	s_cselect_b32 s53, s22, s30
	s_add_u32 s28, s28, 0x40080
	s_addc_u32 s29, s29, 0
	s_add_u32 s54, s30, 0x100
	s_addc_u32 s55, s31, 0
	s_mov_b32 s56, -2
	s_add_u32 s30, s28, 0xfffc0080
	s_addc_u32 s31, s29, -1
	s_add_i32 s57, 0, 0x10000
	s_cmp_eq_u32 s56, 12
	s_cselect_b32 s39, s17, s31
	s_cselect_b32 s38, s25, s30
	s_cselect_b32 s31, s15, s55
	s_cselect_b32 s30, s53, s54
	s_add_i32 s60, 0, 0x14000
	v_add_u32_e32 v156, s57, v145
	v_add_u32_e32 v172, s60, v145
	ds_read_b128 v[140:143], v156
	ds_read_b128 v[148:151], v156 offset:1024
	ds_read_b128 v[152:155], v156 offset:2048
	ds_read_b128 v[156:159], v156 offset:3072
	ds_read_b128 v[160:163], v172
	ds_read_b128 v[164:167], v172 offset:1024
	ds_read_b128 v[168:171], v172 offset:2048
	ds_read_b128 v[172:175], v172 offset:3072
	v_lshl_add_u64 v[208:209], s[28:29], 0, v[136:137]
	s_add_i32 m0, s27, 0xc000
	ds_read_b128 v[176:179], v147
	ds_read_b128 v[180:183], v147 offset:1024
	ds_read_b128 v[184:187], v147 offset:2048
	ds_read_b128 v[188:191], v147 offset:3072
	ds_read_b128 v[192:195], v147 offset:4096
	ds_read_b128 v[196:199], v147 offset:5120
	ds_read_b128 v[200:203], v147 offset:6144
	ds_read_b128 v[204:207], v147 offset:7168
	global_load_lds_dwordx4 v[208:209], off
	v_lshl_add_u64 v[208:209], s[28:29], 0, v[138:139]
	s_add_i32 m0, s27, 0xe000
	s_nop 0
	global_load_lds_dwordx4 v[208:209], off
	s_waitcnt vmcnt(8)
	s_waitcnt lgkmcnt(0)
	s_barrier
	s_waitcnt lgkmcnt(0)
	v_mfma_f32_16x16x32_bf16 v[122:125], v[140:143], v[176:179], 0
	v_mfma_f32_16x16x32_bf16 v[122:125], v[148:151], v[180:183], v[122:125]
	v_mfma_f32_16x16x32_bf16 v[114:117], v[156:159], v[180:183], 0
	v_mfma_f32_16x16x32_bf16 v[114:117], v[152:155], v[176:179], v[114:117]
	v_mfma_f32_16x16x32_bf16 v[98:101], v[152:155], v[184:187], 0
	v_mfma_f32_16x16x32_bf16 v[98:101], v[156:159], v[188:191], v[98:101]
	v_mfma_f32_16x16x32_bf16 v[106:109], v[148:151], v[188:191], 0
	v_mfma_f32_16x16x32_bf16 v[106:109], v[140:143], v[184:187], v[106:109]
	v_mfma_f32_16x16x32_bf16 v[90:93], v[140:143], v[192:195], 0
	v_mfma_f32_16x16x32_bf16 v[90:93], v[148:151], v[196:199], v[90:93]
	v_mfma_f32_16x16x32_bf16 v[82:85], v[156:159], v[196:199], 0
	v_mfma_f32_16x16x32_bf16 v[82:85], v[152:155], v[192:195], v[82:85]
	v_mfma_f32_16x16x32_bf16 v[66:69], v[152:155], v[200:203], 0
	v_mfma_f32_16x16x32_bf16 v[66:69], v[156:159], v[204:207], v[66:69]
	v_mfma_f32_16x16x32_bf16 v[74:77], v[148:151], v[204:207], 0
	v_mfma_f32_16x16x32_bf16 v[74:77], v[140:143], v[200:203], v[74:77]
	v_mfma_f32_16x16x32_bf16 v[78:81], v[160:163], v[200:203], 0
	v_mfma_f32_16x16x32_bf16 v[78:81], v[164:167], v[204:207], v[78:81]
	v_mfma_f32_16x16x32_bf16 v[70:73], v[172:175], v[204:207], 0
	v_mfma_f32_16x16x32_bf16 v[70:73], v[168:171], v[200:203], v[70:73]
	v_mfma_f32_16x16x32_bf16 v[86:89], v[168:171], v[192:195], 0
	v_mfma_f32_16x16x32_bf16 v[86:89], v[172:175], v[196:199], v[86:89]
	v_mfma_f32_16x16x32_bf16 v[94:97], v[164:167], v[196:199], 0
	v_mfma_f32_16x16x32_bf16 v[94:97], v[160:163], v[192:195], v[94:97]
	v_mfma_f32_16x16x32_bf16 v[110:113], v[160:163], v[184:187], 0
	v_mfma_f32_16x16x32_bf16 v[110:113], v[164:167], v[188:191], v[110:113]
	v_mfma_f32_16x16x32_bf16 v[102:105], v[172:175], v[188:191], 0
	v_mfma_f32_16x16x32_bf16 v[102:105], v[168:171], v[184:187], v[102:105]
	v_mfma_f32_16x16x32_bf16 v[118:121], v[168:171], v[176:179], 0
	v_mfma_f32_16x16x32_bf16 v[118:121], v[172:175], v[180:183], v[118:121]
	v_mfma_f32_16x16x32_bf16 v[126:129], v[164:167], v[180:183], 0
	v_mfma_f32_16x16x32_bf16 v[126:129], v[160:163], v[176:179], v[126:129]
	s_barrier
	s_add_i32 s57, s57, s43
	v_lshl_add_u64 v[208:209], s[30:31], 0, v[0:1]
	s_mov_b32 m0, s57
	ds_read_b128 v[176:179], v147 offset:16384
	ds_read_b128 v[180:183], v147 offset:17408
	ds_read_b128 v[184:187], v147 offset:18432
	ds_read_b128 v[188:191], v147 offset:19456
	ds_read_b128 v[192:195], v147 offset:20480
	ds_read_b128 v[196:199], v147 offset:21504
	ds_read_b128 v[200:203], v147 offset:22528
	ds_read_b128 v[204:207], v147 offset:23552
	global_load_lds_dwordx4 v[208:209], off
	s_add_i32 m0, s57, 0x2000
	s_add_u32 s58, s30, 0x40000
	v_lshl_add_u64 v[210:211], s[30:31], 0, v[134:135]
	s_addc_u32 s59, s31, 0
	s_add_i32 s57, s60, s43
	global_load_lds_dwordx4 v[210:211], off
	v_lshl_add_u64 v[212:213], s[58:59], 0, v[0:1]
	s_mov_b32 m0, s57
	v_lshl_add_u64 v[214:215], s[38:39], 0, v[132:133]
	global_load_lds_dwordx4 v[212:213], off
	v_lshl_add_u64 v[212:213], s[58:59], 0, v[134:135]
	s_add_i32 m0, s57, 0x2000
	s_nop 0
	global_load_lds_dwordx4 v[212:213], off
	v_lshl_add_u64 v[212:213], s[38:39], 0, v[130:131]
	s_mov_b32 m0, s27
	s_nop 0
	global_load_lds_dwordx4 v[212:213], off
	s_mov_b32 m0, s44
	s_nop 0
	global_load_lds_dwordx4 v[214:215], off
	s_waitcnt vmcnt(8)
	s_waitcnt lgkmcnt(0)
	s_barrier
	s_waitcnt lgkmcnt(0)
	v_mfma_f32_16x16x32_bf16 v[58:61], v[140:143], v[176:179], 0
	v_mfma_f32_16x16x32_bf16 v[58:61], v[148:151], v[180:183], v[58:61]
	v_mfma_f32_16x16x32_bf16 v[50:53], v[156:159], v[180:183], 0
	v_mfma_f32_16x16x32_bf16 v[50:53], v[152:155], v[176:179], v[50:53]
	v_mfma_f32_16x16x32_bf16 v[34:37], v[152:155], v[184:187], 0
	v_mfma_f32_16x16x32_bf16 v[34:37], v[156:159], v[188:191], v[34:37]
	v_mfma_f32_16x16x32_bf16 v[42:45], v[148:151], v[188:191], 0
	v_mfma_f32_16x16x32_bf16 v[42:45], v[140:143], v[184:187], v[42:45]
	v_mfma_f32_16x16x32_bf16 v[26:29], v[140:143], v[192:195], 0
	v_mfma_f32_16x16x32_bf16 v[26:29], v[148:151], v[196:199], v[26:29]
	v_mfma_f32_16x16x32_bf16 v[18:21], v[156:159], v[196:199], 0
	v_mfma_f32_16x16x32_bf16 v[18:21], v[152:155], v[192:195], v[18:21]
	v_mfma_f32_16x16x32_bf16 v[6:9], v[152:155], v[200:203], 0
	v_mfma_f32_16x16x32_bf16 v[6:9], v[156:159], v[204:207], v[6:9]
	v_mfma_f32_16x16x32_bf16 v[10:13], v[148:151], v[204:207], 0
	v_mfma_f32_16x16x32_bf16 v[10:13], v[140:143], v[200:203], v[10:13]
	v_mfma_f32_16x16x32_bf16 v[14:17], v[160:163], v[200:203], 0
	v_mfma_f32_16x16x32_bf16 v[14:17], v[164:167], v[204:207], v[14:17]
	v_mfma_f32_16x16x32_bf16 v[2:5], v[172:175], v[204:207], 0
	v_mfma_f32_16x16x32_bf16 v[2:5], v[168:171], v[200:203], v[2:5]
	v_mfma_f32_16x16x32_bf16 v[22:25], v[168:171], v[192:195], 0
	v_mfma_f32_16x16x32_bf16 v[22:25], v[172:175], v[196:199], v[22:25]
	v_mfma_f32_16x16x32_bf16 v[30:33], v[164:167], v[196:199], 0
	v_mfma_f32_16x16x32_bf16 v[30:33], v[160:163], v[192:195], v[30:33]
	v_mfma_f32_16x16x32_bf16 v[46:49], v[160:163], v[184:187], 0
	v_mfma_f32_16x16x32_bf16 v[46:49], v[164:167], v[188:191], v[46:49]
	v_mfma_f32_16x16x32_bf16 v[38:41], v[172:175], v[188:191], 0
	v_mfma_f32_16x16x32_bf16 v[38:41], v[168:171], v[184:187], v[38:41]
	v_mfma_f32_16x16x32_bf16 v[54:57], v[168:171], v[176:179], 0
	v_mfma_f32_16x16x32_bf16 v[54:57], v[172:175], v[180:183], v[54:57]
	v_mfma_f32_16x16x32_bf16 v[62:65], v[164:167], v[180:183], 0
	v_mfma_f32_16x16x32_bf16 v[62:65], v[160:163], v[176:179], v[62:65]
	s_barrier
	s_add_i32 s57, 0, 0x18000
	s_add_i32 s58, 0, 0x1c000
	v_add_u32_e32 v156, s57, v145
	v_add_u32_e32 v172, s58, v145
	ds_read_b128 v[140:143], v156
	ds_read_b128 v[148:151], v156 offset:1024
	ds_read_b128 v[152:155], v156 offset:2048
	ds_read_b128 v[156:159], v156 offset:3072
	ds_read_b128 v[160:163], v172
	ds_read_b128 v[164:167], v172 offset:1024
	ds_read_b128 v[168:171], v172 offset:2048
	ds_read_b128 v[172:175], v172 offset:3072
	s_add_u32 s38, s38, 0x40000
	s_addc_u32 s39, s39, 0
	s_mov_b32 m0, s45
	v_lshl_add_u64 v[216:217], s[38:39], 0, v[130:131]
	ds_read_b128 v[176:179], v147 offset:32768
	ds_read_b128 v[180:183], v147 offset:33792
	ds_read_b128 v[184:187], v147 offset:34816
	ds_read_b128 v[188:191], v147 offset:35840
	ds_read_b128 v[192:195], v147 offset:36864
	ds_read_b128 v[196:199], v147 offset:37888
	ds_read_b128 v[200:203], v147 offset:38912
	ds_read_b128 v[204:207], v147 offset:39936
	global_load_lds_dwordx4 v[216:217], off
	v_lshl_add_u64 v[216:217], s[38:39], 0, v[132:133]
	s_mov_b32 m0, s47
	s_nop 0
	global_load_lds_dwordx4 v[216:217], off
	s_waitcnt vmcnt(8)
	s_waitcnt lgkmcnt(0)
	s_barrier
	s_waitcnt lgkmcnt(0)
	v_mfma_f32_16x16x32_bf16 v[122:125], v[140:143], v[176:179], v[122:125]
	v_mfma_f32_16x16x32_bf16 v[122:125], v[148:151], v[180:183], v[122:125]
	v_mfma_f32_16x16x32_bf16 v[114:117], v[156:159], v[180:183], v[114:117]
	v_mfma_f32_16x16x32_bf16 v[114:117], v[152:155], v[176:179], v[114:117]
	v_mfma_f32_16x16x32_bf16 v[98:101], v[152:155], v[184:187], v[98:101]
	v_mfma_f32_16x16x32_bf16 v[98:101], v[156:159], v[188:191], v[98:101]
	v_mfma_f32_16x16x32_bf16 v[106:109], v[148:151], v[188:191], v[106:109]
	v_mfma_f32_16x16x32_bf16 v[106:109], v[140:143], v[184:187], v[106:109]
	v_mfma_f32_16x16x32_bf16 v[90:93], v[140:143], v[192:195], v[90:93]
	v_mfma_f32_16x16x32_bf16 v[90:93], v[148:151], v[196:199], v[90:93]
	v_mfma_f32_16x16x32_bf16 v[82:85], v[156:159], v[196:199], v[82:85]
	v_mfma_f32_16x16x32_bf16 v[82:85], v[152:155], v[192:195], v[82:85]
	v_mfma_f32_16x16x32_bf16 v[66:69], v[152:155], v[200:203], v[66:69]
	v_mfma_f32_16x16x32_bf16 v[66:69], v[156:159], v[204:207], v[66:69]
	v_mfma_f32_16x16x32_bf16 v[74:77], v[148:151], v[204:207], v[74:77]
	v_mfma_f32_16x16x32_bf16 v[74:77], v[140:143], v[200:203], v[74:77]
	v_mfma_f32_16x16x32_bf16 v[78:81], v[160:163], v[200:203], v[78:81]
	v_mfma_f32_16x16x32_bf16 v[78:81], v[164:167], v[204:207], v[78:81]
	v_mfma_f32_16x16x32_bf16 v[70:73], v[172:175], v[204:207], v[70:73]
	v_mfma_f32_16x16x32_bf16 v[70:73], v[168:171], v[200:203], v[70:73]
	v_mfma_f32_16x16x32_bf16 v[86:89], v[168:171], v[192:195], v[86:89]
	v_mfma_f32_16x16x32_bf16 v[86:89], v[172:175], v[196:199], v[86:89]
	v_mfma_f32_16x16x32_bf16 v[94:97], v[164:167], v[196:199], v[94:97]
	v_mfma_f32_16x16x32_bf16 v[94:97], v[160:163], v[192:195], v[94:97]
	v_mfma_f32_16x16x32_bf16 v[110:113], v[160:163], v[184:187], v[110:113]
	v_mfma_f32_16x16x32_bf16 v[110:113], v[164:167], v[188:191], v[110:113]
	v_mfma_f32_16x16x32_bf16 v[102:105], v[172:175], v[188:191], v[102:105]
	v_mfma_f32_16x16x32_bf16 v[102:105], v[168:171], v[184:187], v[102:105]
	v_mfma_f32_16x16x32_bf16 v[118:121], v[168:171], v[176:179], v[118:121]
	v_mfma_f32_16x16x32_bf16 v[118:121], v[172:175], v[180:183], v[118:121]
	v_mfma_f32_16x16x32_bf16 v[126:129], v[164:167], v[180:183], v[126:129]
	v_mfma_f32_16x16x32_bf16 v[126:129], v[160:163], v[176:179], v[126:129]
	s_barrier
	s_add_i32 s38, s57, s43
	v_lshl_add_u64 v[208:209], v[208:209], 0, s[98:99]
	s_mov_b32 m0, s38
	ds_read_b128 v[176:179], v147 offset:49152
	ds_read_b128 v[180:183], v147 offset:50176
	ds_read_b128 v[184:187], v147 offset:51200
	ds_read_b128 v[188:191], v147 offset:52224
	ds_read_b128 v[192:195], v147 offset:53248
	ds_read_b128 v[196:199], v147 offset:54272
	ds_read_b128 v[200:203], v147 offset:55296
	ds_read_b128 v[204:207], v147 offset:56320
	global_load_lds_dwordx4 v[208:209], off
	s_add_i32 m0, s38, 0x2000
	s_add_u32 s30, s30, 0x40080
	v_lshl_add_u64 v[208:209], v[210:211], 0, s[98:99]
	s_addc_u32 s31, s31, 0
	s_add_i32 s38, s58, s43
	global_load_lds_dwordx4 v[208:209], off
	v_lshl_add_u64 v[208:209], s[30:31], 0, v[0:1]
	s_mov_b32 m0, s38
	s_nop 0
	global_load_lds_dwordx4 v[208:209], off
	v_lshl_add_u64 v[208:209], s[30:31], 0, v[134:135]
	s_add_i32 m0, s38, 0x2000
	s_nop 0
	global_load_lds_dwordx4 v[208:209], off
	v_lshl_add_u64 v[208:209], v[212:213], 0, s[98:99]
	s_mov_b32 m0, s49
	s_nop 0
	global_load_lds_dwordx4 v[208:209], off
	v_lshl_add_u64 v[208:209], v[214:215], 0, s[98:99]
	s_mov_b32 m0, s51
	s_nop 0
	global_load_lds_dwordx4 v[208:209], off
	s_waitcnt vmcnt(8)
	s_waitcnt lgkmcnt(0)
	s_barrier
	s_waitcnt lgkmcnt(0)
	v_mfma_f32_16x16x32_bf16 v[58:61], v[140:143], v[176:179], v[58:61]
	v_mfma_f32_16x16x32_bf16 v[58:61], v[148:151], v[180:183], v[58:61]
	v_mfma_f32_16x16x32_bf16 v[50:53], v[156:159], v[180:183], v[50:53]
	v_mfma_f32_16x16x32_bf16 v[50:53], v[152:155], v[176:179], v[50:53]
	v_mfma_f32_16x16x32_bf16 v[34:37], v[152:155], v[184:187], v[34:37]
	v_mfma_f32_16x16x32_bf16 v[34:37], v[156:159], v[188:191], v[34:37]
	v_mfma_f32_16x16x32_bf16 v[42:45], v[148:151], v[188:191], v[42:45]
	v_mfma_f32_16x16x32_bf16 v[42:45], v[140:143], v[184:187], v[42:45]
	v_mfma_f32_16x16x32_bf16 v[26:29], v[140:143], v[192:195], v[26:29]
	v_mfma_f32_16x16x32_bf16 v[26:29], v[148:151], v[196:199], v[26:29]
	v_mfma_f32_16x16x32_bf16 v[18:21], v[156:159], v[196:199], v[18:21]
	v_mfma_f32_16x16x32_bf16 v[18:21], v[152:155], v[192:195], v[18:21]
	v_mfma_f32_16x16x32_bf16 v[6:9], v[152:155], v[200:203], v[6:9]
	v_mfma_f32_16x16x32_bf16 v[6:9], v[156:159], v[204:207], v[6:9]
	v_mfma_f32_16x16x32_bf16 v[10:13], v[148:151], v[204:207], v[10:13]
	v_mfma_f32_16x16x32_bf16 v[10:13], v[140:143], v[200:203], v[10:13]
	v_mfma_f32_16x16x32_bf16 v[14:17], v[160:163], v[200:203], v[14:17]
	v_mfma_f32_16x16x32_bf16 v[14:17], v[164:167], v[204:207], v[14:17]
	v_mfma_f32_16x16x32_bf16 v[2:5], v[172:175], v[204:207], v[2:5]
	v_mfma_f32_16x16x32_bf16 v[2:5], v[168:171], v[200:203], v[2:5]
	v_mfma_f32_16x16x32_bf16 v[22:25], v[168:171], v[192:195], v[22:25]
	v_mfma_f32_16x16x32_bf16 v[22:25], v[172:175], v[196:199], v[22:25]
	v_mfma_f32_16x16x32_bf16 v[30:33], v[164:167], v[196:199], v[30:33]
	v_mfma_f32_16x16x32_bf16 v[30:33], v[160:163], v[192:195], v[30:33]
	v_mfma_f32_16x16x32_bf16 v[46:49], v[160:163], v[184:187], v[46:49]
	v_mfma_f32_16x16x32_bf16 v[46:49], v[164:167], v[188:191], v[46:49]
	v_mfma_f32_16x16x32_bf16 v[38:41], v[172:175], v[188:191], v[38:41]
	v_mfma_f32_16x16x32_bf16 v[38:41], v[168:171], v[184:187], v[38:41]
	v_mfma_f32_16x16x32_bf16 v[54:57], v[168:171], v[176:179], v[54:57]
	v_mfma_f32_16x16x32_bf16 v[54:57], v[172:175], v[180:183], v[54:57]
	v_mfma_f32_16x16x32_bf16 v[62:65], v[164:167], v[180:183], v[62:65]
	v_mfma_f32_16x16x32_bf16 v[62:65], v[160:163], v[176:179], v[62:65]
	s_barrier
	s_add_i32 s56, s56, 2
	s_add_u32 s28, s28, 0x100
	s_addc_u32 s29, s29, 0
	s_add_u32 s54, s54, 0x100
	s_addc_u32 s55, s55, 0
	s_cmp_gt_u32 s56, 13
	s_cbranch_scc1 .Lpeel_done_374
.LBB0_374:
	s_add_u32 s30, s28, 0xfffc0080
	s_addc_u32 s31, s29, -1
	s_add_i32 s57, 0, 0x10000
	s_cmp_eq_u32 s56, 12
	s_cselect_b32 s39, s17, s31
	s_cselect_b32 s38, s25, s30
	s_cselect_b32 s31, s15, s55
	s_cselect_b32 s30, s53, s54
	s_add_i32 s60, 0, 0x14000
	v_add_u32_e32 v156, s57, v145
	v_add_u32_e32 v172, s60, v145
	ds_read_b128 v[140:143], v156
	ds_read_b128 v[148:151], v156 offset:1024
	ds_read_b128 v[152:155], v156 offset:2048
	ds_read_b128 v[156:159], v156 offset:3072
	ds_read_b128 v[160:163], v172
	ds_read_b128 v[164:167], v172 offset:1024
	ds_read_b128 v[168:171], v172 offset:2048
	ds_read_b128 v[172:175], v172 offset:3072
	v_lshl_add_u64 v[208:209], s[28:29], 0, v[136:137]
	s_add_i32 m0, s27, 0xc000
	ds_read_b128 v[176:179], v147
	ds_read_b128 v[180:183], v147 offset:1024
	ds_read_b128 v[184:187], v147 offset:2048
	ds_read_b128 v[188:191], v147 offset:3072
	ds_read_b128 v[192:195], v147 offset:4096
	ds_read_b128 v[196:199], v147 offset:5120
	ds_read_b128 v[200:203], v147 offset:6144
	ds_read_b128 v[204:207], v147 offset:7168
	global_load_lds_dwordx4 v[208:209], off
	v_lshl_add_u64 v[208:209], s[28:29], 0, v[138:139]
	s_add_i32 m0, s27, 0xe000
	s_nop 0
	global_load_lds_dwordx4 v[208:209], off
	s_waitcnt vmcnt(8)
	s_waitcnt lgkmcnt(0)
	s_barrier
	s_waitcnt lgkmcnt(0)
	v_mfma_f32_16x16x32_bf16 v[122:125], v[140:143], v[176:179], v[122:125]
	v_mfma_f32_16x16x32_bf16 v[122:125], v[148:151], v[180:183], v[122:125]
	v_mfma_f32_16x16x32_bf16 v[114:117], v[156:159], v[180:183], v[114:117]
	v_mfma_f32_16x16x32_bf16 v[114:117], v[152:155], v[176:179], v[114:117]
	v_mfma_f32_16x16x32_bf16 v[98:101], v[152:155], v[184:187], v[98:101]
	v_mfma_f32_16x16x32_bf16 v[98:101], v[156:159], v[188:191], v[98:101]
	v_mfma_f32_16x16x32_bf16 v[106:109], v[148:151], v[188:191], v[106:109]
	v_mfma_f32_16x16x32_bf16 v[106:109], v[140:143], v[184:187], v[106:109]
	v_mfma_f32_16x16x32_bf16 v[90:93], v[140:143], v[192:195], v[90:93]
	v_mfma_f32_16x16x32_bf16 v[90:93], v[148:151], v[196:199], v[90:93]
	v_mfma_f32_16x16x32_bf16 v[82:85], v[156:159], v[196:199], v[82:85]
	v_mfma_f32_16x16x32_bf16 v[82:85], v[152:155], v[192:195], v[82:85]
	v_mfma_f32_16x16x32_bf16 v[66:69], v[152:155], v[200:203], v[66:69]
	v_mfma_f32_16x16x32_bf16 v[66:69], v[156:159], v[204:207], v[66:69]
	v_mfma_f32_16x16x32_bf16 v[74:77], v[148:151], v[204:207], v[74:77]
	v_mfma_f32_16x16x32_bf16 v[74:77], v[140:143], v[200:203], v[74:77]
	v_mfma_f32_16x16x32_bf16 v[78:81], v[160:163], v[200:203], v[78:81]
	v_mfma_f32_16x16x32_bf16 v[78:81], v[164:167], v[204:207], v[78:81]
	v_mfma_f32_16x16x32_bf16 v[70:73], v[172:175], v[204:207], v[70:73]
	v_mfma_f32_16x16x32_bf16 v[70:73], v[168:171], v[200:203], v[70:73]
	v_mfma_f32_16x16x32_bf16 v[86:89], v[168:171], v[192:195], v[86:89]
	v_mfma_f32_16x16x32_bf16 v[86:89], v[172:175], v[196:199], v[86:89]
	v_mfma_f32_16x16x32_bf16 v[94:97], v[164:167], v[196:199], v[94:97]
	v_mfma_f32_16x16x32_bf16 v[94:97], v[160:163], v[192:195], v[94:97]
	v_mfma_f32_16x16x32_bf16 v[110:113], v[160:163], v[184:187], v[110:113]
	v_mfma_f32_16x16x32_bf16 v[110:113], v[164:167], v[188:191], v[110:113]
	v_mfma_f32_16x16x32_bf16 v[102:105], v[172:175], v[188:191], v[102:105]
	v_mfma_f32_16x16x32_bf16 v[102:105], v[168:171], v[184:187], v[102:105]
	v_mfma_f32_16x16x32_bf16 v[118:121], v[168:171], v[176:179], v[118:121]
	v_mfma_f32_16x16x32_bf16 v[118:121], v[172:175], v[180:183], v[118:121]
	v_mfma_f32_16x16x32_bf16 v[126:129], v[164:167], v[180:183], v[126:129]
	v_mfma_f32_16x16x32_bf16 v[126:129], v[160:163], v[176:179], v[126:129]
	s_barrier
	s_add_i32 s57, s57, s43
	v_lshl_add_u64 v[208:209], s[30:31], 0, v[0:1]
	s_mov_b32 m0, s57
	ds_read_b128 v[176:179], v147 offset:16384
	ds_read_b128 v[180:183], v147 offset:17408
	ds_read_b128 v[184:187], v147 offset:18432
	ds_read_b128 v[188:191], v147 offset:19456
	ds_read_b128 v[192:195], v147 offset:20480
	ds_read_b128 v[196:199], v147 offset:21504
	ds_read_b128 v[200:203], v147 offset:22528
	ds_read_b128 v[204:207], v147 offset:23552
	global_load_lds_dwordx4 v[208:209], off
	s_add_i32 m0, s57, 0x2000
	s_add_u32 s58, s30, 0x40000
	v_lshl_add_u64 v[210:211], s[30:31], 0, v[134:135]
	s_addc_u32 s59, s31, 0
	s_add_i32 s57, s60, s43
	global_load_lds_dwordx4 v[210:211], off
	v_lshl_add_u64 v[212:213], s[58:59], 0, v[0:1]
	s_mov_b32 m0, s57
	v_lshl_add_u64 v[214:215], s[38:39], 0, v[132:133]
	global_load_lds_dwordx4 v[212:213], off
	v_lshl_add_u64 v[212:213], s[58:59], 0, v[134:135]
	s_add_i32 m0, s57, 0x2000
	s_nop 0
	global_load_lds_dwordx4 v[212:213], off
	v_lshl_add_u64 v[212:213], s[38:39], 0, v[130:131]
	s_mov_b32 m0, s27
	s_nop 0
	global_load_lds_dwordx4 v[212:213], off
	s_mov_b32 m0, s44
	s_nop 0
	global_load_lds_dwordx4 v[214:215], off
	s_waitcnt vmcnt(8)
	s_waitcnt lgkmcnt(0)
	s_barrier
	s_waitcnt lgkmcnt(0)
	v_mfma_f32_16x16x32_bf16 v[58:61], v[140:143], v[176:179], v[58:61]
	v_mfma_f32_16x16x32_bf16 v[58:61], v[148:151], v[180:183], v[58:61]
	v_mfma_f32_16x16x32_bf16 v[50:53], v[156:159], v[180:183], v[50:53]
	v_mfma_f32_16x16x32_bf16 v[50:53], v[152:155], v[176:179], v[50:53]
	v_mfma_f32_16x16x32_bf16 v[34:37], v[152:155], v[184:187], v[34:37]
	v_mfma_f32_16x16x32_bf16 v[34:37], v[156:159], v[188:191], v[34:37]
	v_mfma_f32_16x16x32_bf16 v[42:45], v[148:151], v[188:191], v[42:45]
	v_mfma_f32_16x16x32_bf16 v[42:45], v[140:143], v[184:187], v[42:45]
	v_mfma_f32_16x16x32_bf16 v[26:29], v[140:143], v[192:195], v[26:29]
	v_mfma_f32_16x16x32_bf16 v[26:29], v[148:151], v[196:199], v[26:29]
	v_mfma_f32_16x16x32_bf16 v[18:21], v[156:159], v[196:199], v[18:21]
	v_mfma_f32_16x16x32_bf16 v[18:21], v[152:155], v[192:195], v[18:21]
	v_mfma_f32_16x16x32_bf16 v[6:9], v[152:155], v[200:203], v[6:9]
	v_mfma_f32_16x16x32_bf16 v[6:9], v[156:159], v[204:207], v[6:9]
	v_mfma_f32_16x16x32_bf16 v[10:13], v[148:151], v[204:207], v[10:13]
	v_mfma_f32_16x16x32_bf16 v[10:13], v[140:143], v[200:203], v[10:13]
	v_mfma_f32_16x16x32_bf16 v[14:17], v[160:163], v[200:203], v[14:17]
	v_mfma_f32_16x16x32_bf16 v[14:17], v[164:167], v[204:207], v[14:17]
	v_mfma_f32_16x16x32_bf16 v[2:5], v[172:175], v[204:207], v[2:5]
	v_mfma_f32_16x16x32_bf16 v[2:5], v[168:171], v[200:203], v[2:5]
	v_mfma_f32_16x16x32_bf16 v[22:25], v[168:171], v[192:195], v[22:25]
	v_mfma_f32_16x16x32_bf16 v[22:25], v[172:175], v[196:199], v[22:25]
	v_mfma_f32_16x16x32_bf16 v[30:33], v[164:167], v[196:199], v[30:33]
	v_mfma_f32_16x16x32_bf16 v[30:33], v[160:163], v[192:195], v[30:33]
	v_mfma_f32_16x16x32_bf16 v[46:49], v[160:163], v[184:187], v[46:49]
	v_mfma_f32_16x16x32_bf16 v[46:49], v[164:167], v[188:191], v[46:49]
	v_mfma_f32_16x16x32_bf16 v[38:41], v[172:175], v[188:191], v[38:41]
	v_mfma_f32_16x16x32_bf16 v[38:41], v[168:171], v[184:187], v[38:41]
	v_mfma_f32_16x16x32_bf16 v[54:57], v[168:171], v[176:179], v[54:57]
	v_mfma_f32_16x16x32_bf16 v[54:57], v[172:175], v[180:183], v[54:57]
	v_mfma_f32_16x16x32_bf16 v[62:65], v[164:167], v[180:183], v[62:65]
	v_mfma_f32_16x16x32_bf16 v[62:65], v[160:163], v[176:179], v[62:65]
	s_barrier
	s_add_i32 s57, 0, 0x18000
	s_add_i32 s58, 0, 0x1c000
	v_add_u32_e32 v156, s57, v145
	v_add_u32_e32 v172, s58, v145
	ds_read_b128 v[140:143], v156
	ds_read_b128 v[148:151], v156 offset:1024
	ds_read_b128 v[152:155], v156 offset:2048
	ds_read_b128 v[156:159], v156 offset:3072
	ds_read_b128 v[160:163], v172
	ds_read_b128 v[164:167], v172 offset:1024
	ds_read_b128 v[168:171], v172 offset:2048
	ds_read_b128 v[172:175], v172 offset:3072
	s_add_u32 s38, s38, 0x40000
	s_addc_u32 s39, s39, 0
	s_mov_b32 m0, s45
	v_lshl_add_u64 v[216:217], s[38:39], 0, v[130:131]
	ds_read_b128 v[176:179], v147 offset:32768
	ds_read_b128 v[180:183], v147 offset:33792
	ds_read_b128 v[184:187], v147 offset:34816
	ds_read_b128 v[188:191], v147 offset:35840
	ds_read_b128 v[192:195], v147 offset:36864
	ds_read_b128 v[196:199], v147 offset:37888
	ds_read_b128 v[200:203], v147 offset:38912
	ds_read_b128 v[204:207], v147 offset:39936
	global_load_lds_dwordx4 v[216:217], off
	v_lshl_add_u64 v[216:217], s[38:39], 0, v[132:133]
	s_mov_b32 m0, s47
	s_nop 0
	global_load_lds_dwordx4 v[216:217], off
	s_waitcnt vmcnt(8)
	s_waitcnt lgkmcnt(0)
	s_barrier
	s_waitcnt lgkmcnt(0)
	v_mfma_f32_16x16x32_bf16 v[122:125], v[140:143], v[176:179], v[122:125]
	v_mfma_f32_16x16x32_bf16 v[122:125], v[148:151], v[180:183], v[122:125]
	v_mfma_f32_16x16x32_bf16 v[114:117], v[156:159], v[180:183], v[114:117]
	v_mfma_f32_16x16x32_bf16 v[114:117], v[152:155], v[176:179], v[114:117]
	v_mfma_f32_16x16x32_bf16 v[98:101], v[152:155], v[184:187], v[98:101]
	v_mfma_f32_16x16x32_bf16 v[98:101], v[156:159], v[188:191], v[98:101]
	v_mfma_f32_16x16x32_bf16 v[106:109], v[148:151], v[188:191], v[106:109]
	v_mfma_f32_16x16x32_bf16 v[106:109], v[140:143], v[184:187], v[106:109]
	v_mfma_f32_16x16x32_bf16 v[90:93], v[140:143], v[192:195], v[90:93]
	v_mfma_f32_16x16x32_bf16 v[90:93], v[148:151], v[196:199], v[90:93]
	v_mfma_f32_16x16x32_bf16 v[82:85], v[156:159], v[196:199], v[82:85]
	v_mfma_f32_16x16x32_bf16 v[82:85], v[152:155], v[192:195], v[82:85]
	v_mfma_f32_16x16x32_bf16 v[66:69], v[152:155], v[200:203], v[66:69]
	v_mfma_f32_16x16x32_bf16 v[66:69], v[156:159], v[204:207], v[66:69]
	v_mfma_f32_16x16x32_bf16 v[74:77], v[148:151], v[204:207], v[74:77]
	v_mfma_f32_16x16x32_bf16 v[74:77], v[140:143], v[200:203], v[74:77]
	v_mfma_f32_16x16x32_bf16 v[78:81], v[160:163], v[200:203], v[78:81]
	v_mfma_f32_16x16x32_bf16 v[78:81], v[164:167], v[204:207], v[78:81]
	v_mfma_f32_16x16x32_bf16 v[70:73], v[172:175], v[204:207], v[70:73]
	v_mfma_f32_16x16x32_bf16 v[70:73], v[168:171], v[200:203], v[70:73]
	v_mfma_f32_16x16x32_bf16 v[86:89], v[168:171], v[192:195], v[86:89]
	v_mfma_f32_16x16x32_bf16 v[86:89], v[172:175], v[196:199], v[86:89]
	v_mfma_f32_16x16x32_bf16 v[94:97], v[164:167], v[196:199], v[94:97]
	v_mfma_f32_16x16x32_bf16 v[94:97], v[160:163], v[192:195], v[94:97]
	v_mfma_f32_16x16x32_bf16 v[110:113], v[160:163], v[184:187], v[110:113]
	v_mfma_f32_16x16x32_bf16 v[110:113], v[164:167], v[188:191], v[110:113]
	v_mfma_f32_16x16x32_bf16 v[102:105], v[172:175], v[188:191], v[102:105]
	v_mfma_f32_16x16x32_bf16 v[102:105], v[168:171], v[184:187], v[102:105]
	v_mfma_f32_16x16x32_bf16 v[118:121], v[168:171], v[176:179], v[118:121]
	v_mfma_f32_16x16x32_bf16 v[118:121], v[172:175], v[180:183], v[118:121]
	v_mfma_f32_16x16x32_bf16 v[126:129], v[164:167], v[180:183], v[126:129]
	v_mfma_f32_16x16x32_bf16 v[126:129], v[160:163], v[176:179], v[126:129]
	s_barrier
	s_add_i32 s38, s57, s43
	v_lshl_add_u64 v[208:209], v[208:209], 0, s[98:99]
	s_mov_b32 m0, s38
	ds_read_b128 v[176:179], v147 offset:49152
	ds_read_b128 v[180:183], v147 offset:50176
	ds_read_b128 v[184:187], v147 offset:51200
	ds_read_b128 v[188:191], v147 offset:52224
	ds_read_b128 v[192:195], v147 offset:53248
	ds_read_b128 v[196:199], v147 offset:54272
	ds_read_b128 v[200:203], v147 offset:55296
	ds_read_b128 v[204:207], v147 offset:56320
	global_load_lds_dwordx4 v[208:209], off
	s_add_i32 m0, s38, 0x2000
	s_add_u32 s30, s30, 0x40080
	v_lshl_add_u64 v[208:209], v[210:211], 0, s[98:99]
	s_addc_u32 s31, s31, 0
	s_add_i32 s38, s58, s43
	global_load_lds_dwordx4 v[208:209], off
	v_lshl_add_u64 v[208:209], s[30:31], 0, v[0:1]
	s_mov_b32 m0, s38
	s_nop 0
	global_load_lds_dwordx4 v[208:209], off
	v_lshl_add_u64 v[208:209], s[30:31], 0, v[134:135]
	s_add_i32 m0, s38, 0x2000
	s_nop 0
	global_load_lds_dwordx4 v[208:209], off
	v_lshl_add_u64 v[208:209], v[212:213], 0, s[98:99]
	s_mov_b32 m0, s49
	s_nop 0
	global_load_lds_dwordx4 v[208:209], off
	v_lshl_add_u64 v[208:209], v[214:215], 0, s[98:99]
	s_mov_b32 m0, s51
	s_nop 0
	global_load_lds_dwordx4 v[208:209], off
	s_waitcnt vmcnt(8)
	s_waitcnt lgkmcnt(0)
	s_barrier
	s_waitcnt lgkmcnt(0)
	v_mfma_f32_16x16x32_bf16 v[58:61], v[140:143], v[176:179], v[58:61]
	v_mfma_f32_16x16x32_bf16 v[58:61], v[148:151], v[180:183], v[58:61]
	v_mfma_f32_16x16x32_bf16 v[50:53], v[156:159], v[180:183], v[50:53]
	v_mfma_f32_16x16x32_bf16 v[50:53], v[152:155], v[176:179], v[50:53]
	v_mfma_f32_16x16x32_bf16 v[34:37], v[152:155], v[184:187], v[34:37]
	v_mfma_f32_16x16x32_bf16 v[34:37], v[156:159], v[188:191], v[34:37]
	v_mfma_f32_16x16x32_bf16 v[42:45], v[148:151], v[188:191], v[42:45]
	v_mfma_f32_16x16x32_bf16 v[42:45], v[140:143], v[184:187], v[42:45]
	v_mfma_f32_16x16x32_bf16 v[26:29], v[140:143], v[192:195], v[26:29]
	v_mfma_f32_16x16x32_bf16 v[26:29], v[148:151], v[196:199], v[26:29]
	v_mfma_f32_16x16x32_bf16 v[18:21], v[156:159], v[196:199], v[18:21]
	v_mfma_f32_16x16x32_bf16 v[18:21], v[152:155], v[192:195], v[18:21]
	v_mfma_f32_16x16x32_bf16 v[6:9], v[152:155], v[200:203], v[6:9]
	v_mfma_f32_16x16x32_bf16 v[6:9], v[156:159], v[204:207], v[6:9]
	v_mfma_f32_16x16x32_bf16 v[10:13], v[148:151], v[204:207], v[10:13]
	v_mfma_f32_16x16x32_bf16 v[10:13], v[140:143], v[200:203], v[10:13]
	v_mfma_f32_16x16x32_bf16 v[14:17], v[160:163], v[200:203], v[14:17]
	v_mfma_f32_16x16x32_bf16 v[14:17], v[164:167], v[204:207], v[14:17]
	v_mfma_f32_16x16x32_bf16 v[2:5], v[172:175], v[204:207], v[2:5]
	v_mfma_f32_16x16x32_bf16 v[2:5], v[168:171], v[200:203], v[2:5]
	v_mfma_f32_16x16x32_bf16 v[22:25], v[168:171], v[192:195], v[22:25]
	v_mfma_f32_16x16x32_bf16 v[22:25], v[172:175], v[196:199], v[22:25]
	v_mfma_f32_16x16x32_bf16 v[30:33], v[164:167], v[196:199], v[30:33]
	v_mfma_f32_16x16x32_bf16 v[30:33], v[160:163], v[192:195], v[30:33]
	v_mfma_f32_16x16x32_bf16 v[46:49], v[160:163], v[184:187], v[46:49]
	v_mfma_f32_16x16x32_bf16 v[46:49], v[164:167], v[188:191], v[46:49]
	v_mfma_f32_16x16x32_bf16 v[38:41], v[172:175], v[188:191], v[38:41]
	v_mfma_f32_16x16x32_bf16 v[38:41], v[168:171], v[184:187], v[38:41]
	v_mfma_f32_16x16x32_bf16 v[54:57], v[168:171], v[176:179], v[54:57]
	v_mfma_f32_16x16x32_bf16 v[54:57], v[172:175], v[180:183], v[54:57]
	v_mfma_f32_16x16x32_bf16 v[62:65], v[164:167], v[180:183], v[62:65]
	v_mfma_f32_16x16x32_bf16 v[62:65], v[160:163], v[176:179], v[62:65]
	s_barrier
	s_add_i32 s56, s56, 2
	s_add_u32 s28, s28, 0x100
	s_addc_u32 s29, s29, 0
	s_add_u32 s54, s54, 0x100
	s_addc_u32 s55, s55, 0
	s_cmp_gt_u32 s56, 13
	s_cbranch_scc0 .LBB0_374
